# scan waves: y products and k*v / decay updates fill every DPP wait slot (no s_nop fillers); loader waves get their own per-copy loop latch
# speedup vs baseline: 1.0024x; 1.0024x over previous
; #define LAS __attribute__((address_space(3)))
; #define SCAN_LOAD(chn) SCAN_LOAD_RAW()
; __device__ __forceinline__ void phase_scan(const Params& p, LAS unsigned char* lds) {
;     ...
;                     { unsigned m1u_ = 0xBC00BC00u; asm volatile("" : "+s"(m1u_));
;                       typedef unsigned u32x4_ __attribute__((ext_vector_type(4))); const u32x4_ m1v_ = {m1u_, m1u_, m1u_, m1u_}; const h16x8 m1_ = __builtin_bit_cast(h16x8, m1v_);
;                       const h16x8 r8 = pr + mu_r8 * (pr * m1_ + qr_), k8 = pk + mu_k8 * (pk * m1_ + qk_), v8 = pv + mu_v8 * (pv * m1_ + qv_);
;                       const h16x8 w8 = pw + mu_w8 * (pw * m1_ + qw_), a8 = pa + mu_a8 * (pa * m1_ + qa_);
;                       h16x8 tw8;
; #pragma unroll
;                       for (int pi = 0; pi < 4; ++pi) { qr[pi] = (f32x2){(float)r8[2 * pi], (float)r8[2 * pi + 1]}; qk[pi] = (f32x2){(float)k8[2 * pi], (float)k8[2 * pi + 1]};
;                           qv[2 * pi] = (float)v8[2 * pi]; qv[2 * pi + 1] = (float)v8[2 * pi + 1];
;                           const f32x2 tx = (f32x2){(float)w8[2 * pi], (float)w8[2 * pi + 1]} * 2.8853900817779268f;
;                           const f32x2 dn = (f32x2){__builtin_amdgcn_exp2f(tx[0]), __builtin_amdgcn_exp2f(tx[1])} + 1.f;
;                           const f32x2 th = (f32x2){__builtin_amdgcn_rcpf(dn[0]), __builtin_amdgcn_rcpf(dn[1])} * -2.f + 1.f;
;                           tw8[2 * pi] = (h16)th[0]; tw8[2 * pi + 1] = (h16)th[1]; }
;                       *(LAS h16x8*)(TWp + s_sub * 72 + c8) = tw8; *(LAS h16x8*)(QAp + s_sub * 72 + c8) = a8; }
;                     if (cn + 1 < SEQ / 32) SCAN_LOAD(cn + 1);
.Lpa_in:
	s_cmpk_eq_i32 s81, 0xff
	s_cbranch_scc1 .LBB0_608
	s_mov_b32 s14, 0xbc00bc00
	s_cmpk_eq_i32 s81, 0xfe
	s_waitcnt vmcnt(1)
	v_pk_fma_f16 v0, v4, s14, v12
	v_pk_fma_f16 v102, v5, s14, v13
	v_pk_fma_f16 v103, v6, s14, v14
	v_pk_fma_f16 v104, v7, s14, v15
	v_pk_fma_f16 v107, v74, v103, v6
	v_pk_fma_f16 v109, v75, v104, v7
	v_pk_fma_f16 v105, v65, v102, v5
	v_pk_fma_f16 v0, v64, v0, v4
	v_cvt_f32_f16_e32 v104, v105
	v_cvt_f32_f16_e32 v102, v0
	v_cvt_f32_f16_sdwa v103, v0 dst_sel:DWORD dst_unused:UNUSED_PAD src0_sel:WORD_1
	v_cvt_f32_f16_sdwa v105, v105 dst_sel:DWORD dst_unused:UNUSED_PAD src0_sel:WORD_1
	v_cvt_f32_f16_e32 v106, v107
	v_cvt_f32_f16_sdwa v107, v107 dst_sel:DWORD dst_unused:UNUSED_PAD src0_sel:WORD_1
	v_cvt_f32_f16_e32 v108, v109
	v_cvt_f32_f16_sdwa v109, v109 dst_sel:DWORD dst_unused:UNUSED_PAD src0_sel:WORD_1
	v_pk_mul_f32 v[102:103], v[102:103], s[30:31] op_sel_hi:[1,0]
	v_pk_mul_f32 v[104:105], v[104:105], s[30:31] op_sel_hi:[1,0]
	v_pk_mul_f32 v[106:107], v[106:107], s[30:31] op_sel_hi:[1,0]
	v_pk_mul_f32 v[108:109], v[108:109], s[30:31] op_sel_hi:[1,0]
	v_exp_f32_e32 v102, v102
	v_exp_f32_e32 v103, v103
	v_exp_f32_e32 v104, v104
	v_exp_f32_e32 v105, v105
	v_exp_f32_e32 v106, v106
	v_exp_f32_e32 v107, v107
	v_exp_f32_e32 v108, v108
	v_exp_f32_e32 v109, v109
	v_pk_add_f32 v[102:103], v[102:103], 1.0 op_sel_hi:[1,0]
	v_pk_add_f32 v[104:105], v[104:105], 1.0 op_sel_hi:[1,0]
	v_pk_add_f32 v[106:107], v[106:107], 1.0 op_sel_hi:[1,0]
	v_pk_add_f32 v[108:109], v[108:109], 1.0 op_sel_hi:[1,0]
	v_rcp_f32_e32 v102, v102
	v_rcp_f32_e32 v103, v103
	v_rcp_f32_e32 v104, v104
	v_rcp_f32_e32 v105, v105
	v_rcp_f32_e32 v106, v106
	v_rcp_f32_e32 v107, v107
	v_rcp_f32_e32 v108, v108
	v_rcp_f32_e32 v109, v109
	s_waitcnt vmcnt(0)
	v_pk_fma_f16 v112, v8, s14, v16
	v_pk_fma_f16 v113, v9, s14, v17
	v_pk_fma_f16 v114, v10, s14, v18
	v_pk_fma_f16 v0, v11, s14, v19
	v_pk_fma_f32 v[110:111], v[102:103], 2.0, 1.0 op_sel_hi:[1,0,0] neg_lo:[1,0,0] neg_hi:[1,0,0]
	v_pk_fma_f32 v[102:103], v[104:105], 2.0, 1.0 op_sel_hi:[1,0,0] neg_lo:[1,0,0] neg_hi:[1,0,0]
	v_pk_fma_f32 v[106:107], v[106:107], 2.0, 1.0 op_sel_hi:[1,0,0] neg_lo:[1,0,0] neg_hi:[1,0,0]
	v_pk_fma_f32 v[104:105], v[108:109], 2.0, 1.0 op_sel_hi:[1,0,0] neg_lo:[1,0,0] neg_hi:[1,0,0]
	v_cvt_pk_f16_f32 v103, v102, v103
	v_cvt_pk_f16_f32 v105, v104, v105
	v_cvt_pk_f16_f32 v104, v106, v107
	v_cvt_pk_f16_f32 v102, v110, v111
	v_pk_fma_f16 v109, v77, v0, v11
	v_pk_fma_f16 v108, v76, v114, v10
	v_pk_fma_f16 v107, v67, v113, v9
	v_pk_fma_f16 v106, v66, v112, v8
	ds_write_b128 v171, v[102:105] offset:18432
	ds_write_b128 v172, v[106:109] offset:19584
	s_cbranch_scc1 .LBB0_609
	v_lshl_add_u64 v[4:5], v[148:149], 0, s[20:21]
	global_load_dwordx4 v[118:121], v[146:147], off
	global_load_dwordx4 v[110:113], v[146:147], off offset:2048
	global_load_dwordx4 v[102:105], v[4:5], off
	s_nop 0
	global_load_dwordx4 v[4:7], v[148:149], off offset:2048
	global_load_dwordx4 v[8:11], v[148:149], off offset:2176
	global_load_dwordx4 v[122:125], v[152:153], off
	global_load_dwordx4 v[114:117], v[152:153], off offset:2048
	v_lshl_add_u64 v[12:13], v[150:151], 0, s[20:21]
	global_load_dwordx4 v[106:109], v[12:13], off
	s_nop 0
	global_load_dwordx4 v[12:15], v[150:151], off offset:2048
	global_load_dwordx4 v[16:19], v[150:151], off offset:2176
	s_lshl_b64 s[34:35], s[46:47], 1
	v_lshl_add_u64 v[146:147], v[146:147], 0, s[34:35]
	v_lshl_add_u64 v[148:149], v[148:149], 0, s[34:35]
	s_lshl_b64 s[34:35], s[40:41], 1
	v_lshl_add_u64 v[152:153], v[146:147], 0, s[34:35]
	v_lshl_add_u64 v[150:151], v[148:149], 0, s[34:35]
	s_branch .LBB0_610

; #define LDS_BAR() do { asm volatile("s_waitcnt lgkmcnt(0)" ::: "memory"); __builtin_amdgcn_s_barrier(); asm volatile("" ::: "memory"); } while (0)
; __device__ __forceinline__ void phase_scan(const Params& p, LAS unsigned char* lds) {
;     ...
;                 if (n >= 1) SCAN_YSTORE(n - 1);
;             }
;             LDS_BAR();
;         }
.LBB0_616:
.LBB0_617:
	s_waitcnt lgkmcnt(0)
	s_barrier
	s_add_i32 s81, s81, 1
	s_addk_i32 s82, 0x200
	v_add_u32_e32 v145, 32, v145
	s_cmpk_eq_i32 s81, 0x100
	v_subrev_u32_e32 v162, 32, v162
	s_cbranch_scc1 .LBB0_620
	s_waitcnt vmcnt(2)
	s_branch .Lpb_in

; #define LAS __attribute__((address_space(3)))
; #define SCAN_LOAD(chn) SCAN_LOAD_RAW()
; __device__ __forceinline__ void phase_scan(const Params& p, LAS unsigned char* lds) {
;     ...
;                     { unsigned m1u_ = 0xBC00BC00u; asm volatile("" : "+s"(m1u_));
;                       typedef unsigned u32x4_ __attribute__((ext_vector_type(4))); const u32x4_ m1v_ = {m1u_, m1u_, m1u_, m1u_}; const h16x8 m1_ = __builtin_bit_cast(h16x8, m1v_);
;                       const h16x8 r8 = pr + mu_r8 * (pr * m1_ + qr_), k8 = pk + mu_k8 * (pk * m1_ + qk_), v8 = pv + mu_v8 * (pv * m1_ + qv_);
;                       const h16x8 w8 = pw + mu_w8 * (pw * m1_ + qw_), a8 = pa + mu_a8 * (pa * m1_ + qa_);
;                       h16x8 tw8;
; #pragma unroll
;                       for (int pi = 0; pi < 4; ++pi) { qr[pi] = (f32x2){(float)r8[2 * pi], (float)r8[2 * pi + 1]}; qk[pi] = (f32x2){(float)k8[2 * pi], (float)k8[2 * pi + 1]};
;                           qv[2 * pi] = (float)v8[2 * pi]; qv[2 * pi + 1] = (float)v8[2 * pi + 1];
;                           const f32x2 tx = (f32x2){(float)w8[2 * pi], (float)w8[2 * pi + 1]} * 2.8853900817779268f;
;                           const f32x2 dn = (f32x2){__builtin_amdgcn_exp2f(tx[0]), __builtin_amdgcn_exp2f(tx[1])} + 1.f;
;                           const f32x2 th = (f32x2){__builtin_amdgcn_rcpf(dn[0]), __builtin_amdgcn_rcpf(dn[1])} * -2.f + 1.f;
;                           tw8[2 * pi] = (h16)th[0]; tw8[2 * pi + 1] = (h16)th[1]; }
;                       *(LAS h16x8*)(TWp + s_sub * 72 + c8) = tw8; *(LAS h16x8*)(QAp + s_sub * 72 + c8) = a8; }
;                     if (cn + 1 < SEQ / 32) SCAN_LOAD(cn + 1);
.Lpb_in:
	s_cmpk_eq_i32 s81, 0xff
	s_cbranch_scc1 .Lpb_608
	s_mov_b32 s14, 0xbc00bc00
	s_cmpk_eq_i32 s81, 0xfe
	s_waitcnt vmcnt(1)
	v_pk_fma_f16 v0, v4, s14, v12
	v_pk_fma_f16 v78, v5, s14, v13
	v_pk_fma_f16 v79, v6, s14, v14
	v_pk_fma_f16 v80, v7, s14, v15
	v_pk_fma_f16 v83, v74, v79, v6
	v_pk_fma_f16 v85, v75, v80, v7
	v_pk_fma_f16 v81, v65, v78, v5
	v_pk_fma_f16 v0, v64, v0, v4
	v_cvt_f32_f16_e32 v80, v81
	v_cvt_f32_f16_e32 v78, v0
	v_cvt_f32_f16_sdwa v79, v0 dst_sel:DWORD dst_unused:UNUSED_PAD src0_sel:WORD_1
	v_cvt_f32_f16_sdwa v81, v81 dst_sel:DWORD dst_unused:UNUSED_PAD src0_sel:WORD_1
	v_cvt_f32_f16_e32 v82, v83
	v_cvt_f32_f16_sdwa v83, v83 dst_sel:DWORD dst_unused:UNUSED_PAD src0_sel:WORD_1
	v_cvt_f32_f16_e32 v84, v85
	v_cvt_f32_f16_sdwa v85, v85 dst_sel:DWORD dst_unused:UNUSED_PAD src0_sel:WORD_1
	v_pk_mul_f32 v[78:79], v[78:79], s[30:31] op_sel_hi:[1,0]
	v_pk_mul_f32 v[80:81], v[80:81], s[30:31] op_sel_hi:[1,0]
	v_pk_mul_f32 v[82:83], v[82:83], s[30:31] op_sel_hi:[1,0]
	v_pk_mul_f32 v[84:85], v[84:85], s[30:31] op_sel_hi:[1,0]
	v_exp_f32_e32 v78, v78
	v_exp_f32_e32 v79, v79
	v_exp_f32_e32 v80, v80
	v_exp_f32_e32 v81, v81
	v_exp_f32_e32 v82, v82
	v_exp_f32_e32 v83, v83
	v_exp_f32_e32 v84, v84
	v_exp_f32_e32 v85, v85
	v_pk_add_f32 v[78:79], v[78:79], 1.0 op_sel_hi:[1,0]
	v_pk_add_f32 v[80:81], v[80:81], 1.0 op_sel_hi:[1,0]
	v_pk_add_f32 v[82:83], v[82:83], 1.0 op_sel_hi:[1,0]
	v_pk_add_f32 v[84:85], v[84:85], 1.0 op_sel_hi:[1,0]
	v_rcp_f32_e32 v78, v78
	v_rcp_f32_e32 v79, v79
	v_rcp_f32_e32 v80, v80
	v_rcp_f32_e32 v81, v81
	v_rcp_f32_e32 v82, v82
	v_rcp_f32_e32 v83, v83
	v_rcp_f32_e32 v84, v84
	v_rcp_f32_e32 v85, v85
	s_waitcnt vmcnt(0)
	v_pk_fma_f16 v88, v8, s14, v16
	v_pk_fma_f16 v89, v9, s14, v17
	v_pk_fma_f16 v90, v10, s14, v18
	v_pk_fma_f16 v0, v11, s14, v19
	v_pk_fma_f32 v[86:87], v[78:79], 2.0, 1.0 op_sel_hi:[1,0,0] neg_lo:[1,0,0] neg_hi:[1,0,0]
	v_pk_fma_f32 v[78:79], v[80:81], 2.0, 1.0 op_sel_hi:[1,0,0] neg_lo:[1,0,0] neg_hi:[1,0,0]
	v_pk_fma_f32 v[82:83], v[82:83], 2.0, 1.0 op_sel_hi:[1,0,0] neg_lo:[1,0,0] neg_hi:[1,0,0]
	v_pk_fma_f32 v[80:81], v[84:85], 2.0, 1.0 op_sel_hi:[1,0,0] neg_lo:[1,0,0] neg_hi:[1,0,0]
	v_cvt_pk_f16_f32 v79, v78, v79
	v_cvt_pk_f16_f32 v81, v80, v81
	v_cvt_pk_f16_f32 v80, v82, v83
	v_cvt_pk_f16_f32 v78, v86, v87
	v_pk_fma_f16 v85, v77, v0, v11
	v_pk_fma_f16 v84, v76, v90, v10
	v_pk_fma_f16 v83, v67, v89, v9
	v_pk_fma_f16 v82, v66, v88, v8
	ds_write_b128 v171, v[78:81] offset:18432
	ds_write_b128 v172, v[82:85] offset:19584
	s_cbranch_scc1 .Lpb_609
	v_lshl_add_u64 v[4:5], v[148:149], 0, s[20:21]
	global_load_dwordx4 v[94:97], v[146:147], off
	global_load_dwordx4 v[86:89], v[146:147], off offset:2048
	global_load_dwordx4 v[78:81], v[4:5], off
	s_nop 0
	global_load_dwordx4 v[4:7], v[148:149], off offset:2048
	global_load_dwordx4 v[8:11], v[148:149], off offset:2176
	global_load_dwordx4 v[98:101], v[152:153], off
	global_load_dwordx4 v[90:93], v[152:153], off offset:2048
	v_lshl_add_u64 v[12:13], v[150:151], 0, s[20:21]
	global_load_dwordx4 v[82:85], v[12:13], off
	s_nop 0
	global_load_dwordx4 v[12:15], v[150:151], off offset:2048
	global_load_dwordx4 v[16:19], v[150:151], off offset:2176
	s_lshl_b64 s[34:35], s[46:47], 1
	v_lshl_add_u64 v[146:147], v[146:147], 0, s[34:35]
	v_lshl_add_u64 v[148:149], v[148:149], 0, s[34:35]
	s_lshl_b64 s[34:35], s[40:41], 1
	v_lshl_add_u64 v[152:153], v[146:147], 0, s[34:35]
	v_lshl_add_u64 v[150:151], v[148:149], 0, s[34:35]
	s_branch .Lpb_610

; __device__ __forceinline__ void phase_scan(const Params& p, LAS unsigned char* lds) {
;     ...
;                     const LAS float* sR = OPS + (n & 1) * SET_F + j0; const LAS float* sW = sR + 2048; const LAS float* sK = sW + 2048; const LAS float* sA = sK + 2048; const LAS float* sB = sA + 2048; const LAS float* sV = OPS + (n & 1) * SET_F + 10240;
;                     LAS float* sY = sYb + (n & 1) * 512;
;                     f32x4 a_ = *(const LAS f32x4*)(sA), w_ = *(const LAS f32x4*)(sW), b_ = *(const LAS f32x4*)(sB);
;                     f32x4 k_ = *(const LAS f32x4*)(sK), r_ = *(const LAS f32x4*)(sR);
;                     f32x4 vq[4];
; #pragma unroll
;                     for (int u = 0; u < 4; ++u) vq[u] = *(const LAS f32x4*)(sV + srow * 32 + 4 * u);
;                     f32x4 rp = r_;
; #pragma unroll
;                     for (int hb = 0; hb < 2; ++hb) {
;                         f32x4 vn[4];
; #pragma unroll
;                         for (int u = 0; u < 4; ++u) vn[u] = *(const LAS f32x4*)(sV + srow * 32 + ((16 * (hb + 1)) & 31) + 4 * u);
; #pragma unroll
;                         for (int u16 = 0; u16 < 16; ++u16) {
;                             const int s = 16 * hb + u16;
;                             const int sn = (s + 1) & 31;
;                             const f32x4 a_n = *(const LAS f32x4*)(sA + sn * 64), w_n = *(const LAS f32x4*)(sW + sn * 64), b_n = *(const LAS f32x4*)(sB + sn * 64);
;                             const f32x4 k_n = *(const LAS f32x4*)(sK + sn * 64), r_n = *(const LAS f32x4*)(sR + sn * 64);
;                             const float v = vq[u16 >> 2][u16 & 3];
;                             const f32x2 vv = {v, v};
;                             f32x2 pp = S01 * (f32x2){a_[0], a_[1]}; pp = S23 * (f32x2){a_[2], a_[3]} + pp;
;                             f32x2 yy = S01 * (f32x2){rp[0], rp[1]}; yy = S23 * (f32x2){rp[2], rp[3]} + yy;
;                             float sa = pp[0] + pp[1], y = yy[0] + yy[1];
;                             sa += dpp_f<0xB1>(sa); y += dpp_f<0xB1>(y);
;                             sa += dpp_f<0x4E>(sa); y += dpp_f<0x4E>(y);
;                             sa += dpp_f<0x141>(sa); y += dpp_f<0x141>(y);
;                             sa += dpp_f<0x140>(sa); y += dpp_f<0x140>(y);
;                             sY[((s - 1) & 31) * 16 + srow] = y;
;                             const f32x2 sv = {sa, sa};
.Lscan_trip:
	s_and_b32 s14, s81, 1
	s_mul_i32 s15, s14, 0xa800
	s_add_i32 s15, s15, 0x8800
	v_add_u32_e32 v124, s15, v178
	v_add_u32_e32 v125, s15, v179
	s_cmp_eq_u32 s81, 0
	s_cselect_b32 s14, 0xc000c000, -1
	s_mov_b32 s15, s14
	v_pk_mul_f32 v[114:115], v[166:167], v[22:23]
	v_pk_fma_f32 v[114:115], v[164:165], v[24:25], v[114:115]
	v_add_f32_e32 v122, v114, v115
	v_pk_mul_f32 v[116:117], v[166:167], v[18:19]
	v_pk_mul_f32 v[118:119], v[110:111], v[34:35] op_sel:[1,0]
	v_add_f32_dpp v122, v122, v122 quad_perm:[1,0,3,2] row_mask:0xf bank_mask:0xf bound_ctrl:1
	v_pk_fma_f32 v[116:117], v[164:165], v[20:21], v[116:117]
	v_pk_mul_f32 v[120:121], v[110:111], v[36:37] op_sel:[1,0]
	v_add_f32_dpp v122, v122, v122 quad_perm:[2,3,0,1] row_mask:0xf bank_mask:0xf bound_ctrl:1
	v_add_f32_e32 v214, v116, v117
	v_pk_fma_f32 v[166:167], v[166:167], v[26:27], v[118:119]
	v_add_f32_dpp v122, v122, v122 row_half_mirror row_mask:0xf bank_mask:0xf bound_ctrl:1
	v_pk_fma_f32 v[164:165], v[164:165], v[28:29], v[120:121]
	v_add_f32_dpp v204, v204, v204 row_mirror row_mask:0xf bank_mask:0xf bound_ctrl:1
	v_add_f32_dpp v122, v122, v122 row_mirror row_mask:0xf bank_mask:0xf bound_ctrl:1
	v_add_f32_dpp v204, v212, v212 row_mirror row_mask:0xf bank_mask:0xc bound_ctrl:1
	v_pk_fma_f32 v[166:167], v[30:31], v[122:123], v[166:167] op_sel_hi:[1,0,1]
	v_pk_fma_f32 v[164:165], v[32:33], v[122:123], v[164:165] op_sel_hi:[1,0,1]
	ds_read_b128 v[14:17], v124 offset:16384
	ds_read_b128 v[6:9], v124 offset:8192
	ds_read_b128 v[10:13], v124 offset:32768
	ds_read_b128 v[18:21], v124 offset:0
	ds_read_b128 v[2:5], v124 offset:24576
	ds_read_b128 v[82:85], v125 offset:40960
	v_add_f32_dpp v205, v205, v205 row_mirror row_mask:0xf bank_mask:0xf bound_ctrl:1
	v_add_f32_dpp v205, v213, v213 row_mirror row_mask:0xf bank_mask:0xc bound_ctrl:1
	v_pk_mul_f32 v[114:115], v[166:167], v[42:43]
	v_pk_fma_f32 v[114:115], v[164:165], v[44:45], v[114:115]
	v_add_f32_e32 v122, v114, v115
	v_pk_mul_f32 v[116:117], v[166:167], v[38:39]
	v_pk_mul_f32 v[118:119], v[112:113], v[54:55] op_sel_hi:[0,1]
	v_add_f32_dpp v122, v122, v122 quad_perm:[1,0,3,2] row_mask:0xf bank_mask:0xf bound_ctrl:1
	v_pk_fma_f32 v[116:117], v[164:165], v[40:41], v[116:117]
	v_pk_mul_f32 v[120:121], v[112:113], v[56:57] op_sel_hi:[0,1]
	v_add_f32_dpp v122, v122, v122 quad_perm:[2,3,0,1] row_mask:0xf bank_mask:0xf bound_ctrl:1
	v_add_f32_e32 v215, v116, v117
	v_pk_fma_f32 v[166:167], v[166:167], v[46:47], v[118:119]
	v_add_f32_dpp v122, v122, v122 row_half_mirror row_mask:0xf bank_mask:0xf bound_ctrl:1
	v_pk_fma_f32 v[164:165], v[164:165], v[48:49], v[120:121]
	v_add_f32_dpp v206, v206, v206 row_mirror row_mask:0xf bank_mask:0xf bound_ctrl:1
	v_add_f32_dpp v122, v122, v122 row_mirror row_mask:0xf bank_mask:0xf bound_ctrl:1
	v_add_f32_dpp v206, v214, v214 row_mirror row_mask:0xf bank_mask:0xc bound_ctrl:1
	v_pk_fma_f32 v[166:167], v[50:51], v[122:123], v[166:167] op_sel_hi:[1,0,1]
	v_pk_fma_f32 v[164:165], v[52:53], v[122:123], v[164:165] op_sel_hi:[1,0,1]
	ds_read_b128 v[34:37], v124 offset:16640
	ds_read_b128 v[26:29], v124 offset:8448
	ds_read_b128 v[30:33], v124 offset:33024
	ds_read_b128 v[38:41], v124 offset:256
	ds_read_b128 v[22:25], v124 offset:24832
	v_add_f32_dpp v207, v207, v207 row_mirror row_mask:0xf bank_mask:0xf bound_ctrl:1
	v_add_f32_dpp v207, v215, v215 row_mirror row_mask:0xf bank_mask:0xc bound_ctrl:1
	v_pk_mul_f32 v[114:115], v[166:167], v[62:63]
	v_pk_fma_f32 v[114:115], v[164:165], v[64:65], v[114:115]
	v_add_f32_e32 v122, v114, v115
	v_pk_mul_f32 v[116:117], v[166:167], v[58:59]
	v_pk_mul_f32 v[118:119], v[112:113], v[74:75] op_sel:[1,0]
	v_add_f32_dpp v122, v122, v122 quad_perm:[1,0,3,2] row_mask:0xf bank_mask:0xf bound_ctrl:1
	v_pk_fma_f32 v[116:117], v[164:165], v[60:61], v[116:117]
	v_pk_mul_f32 v[120:121], v[112:113], v[76:77] op_sel:[1,0]
	v_add_f32_dpp v122, v122, v122 quad_perm:[2,3,0,1] row_mask:0xf bank_mask:0xf bound_ctrl:1
	v_add_f32_e32 v216, v116, v117
	v_pk_fma_f32 v[166:167], v[166:167], v[66:67], v[118:119]
	v_add_f32_dpp v122, v122, v122 row_half_mirror row_mask:0xf bank_mask:0xf bound_ctrl:1
	v_pk_fma_f32 v[164:165], v[164:165], v[68:69], v[120:121]
	v_add_f32_dpp v208, v208, v208 row_mirror row_mask:0xf bank_mask:0xf bound_ctrl:1
	v_add_f32_dpp v122, v122, v122 row_mirror row_mask:0xf bank_mask:0xf bound_ctrl:1
	v_add_f32_dpp v208, v216, v216 row_mirror row_mask:0xf bank_mask:0xc bound_ctrl:1
	v_pk_fma_f32 v[166:167], v[70:71], v[122:123], v[166:167] op_sel_hi:[1,0,1]
	v_pk_fma_f32 v[164:165], v[72:73], v[122:123], v[164:165] op_sel_hi:[1,0,1]
	ds_read_b128 v[54:57], v124 offset:16896
	ds_read_b128 v[46:49], v124 offset:8704
	ds_read_b128 v[50:53], v124 offset:33280
	ds_read_b128 v[58:61], v124 offset:512
	ds_read_b128 v[42:45], v124 offset:25088
	s_waitcnt lgkmcnt(11)
	v_pk_mul_f32 v[114:115], v[166:167], v[2:3]
	v_pk_fma_f32 v[114:115], v[164:165], v[4:5], v[114:115]
	v_add_f32_e32 v122, v114, v115
	v_pk_mul_f32 v[116:117], v[166:167], v[78:79]
	s_waitcnt lgkmcnt(10)
	v_pk_mul_f32 v[118:119], v[82:83], v[14:15] op_sel_hi:[0,1]
	v_add_f32_dpp v122, v122, v122 quad_perm:[1,0,3,2] row_mask:0xf bank_mask:0xf bound_ctrl:1
	v_pk_fma_f32 v[116:117], v[164:165], v[80:81], v[116:117]
	v_pk_mul_f32 v[120:121], v[82:83], v[16:17] op_sel_hi:[0,1]
	v_add_f32_dpp v122, v122, v122 quad_perm:[2,3,0,1] row_mask:0xf bank_mask:0xf bound_ctrl:1
	v_add_f32_e32 v217, v116, v117
	v_pk_fma_f32 v[166:167], v[166:167], v[6:7], v[118:119]
	v_add_f32_dpp v122, v122, v122 row_half_mirror row_mask:0xf bank_mask:0xf bound_ctrl:1
	v_pk_fma_f32 v[164:165], v[164:165], v[8:9], v[120:121]
	v_add_f32_dpp v209, v209, v209 row_mirror row_mask:0xf bank_mask:0xf bound_ctrl:1
	v_add_f32_dpp v122, v122, v122 row_mirror row_mask:0xf bank_mask:0xf bound_ctrl:1
	v_add_f32_dpp v209, v217, v217 row_mirror row_mask:0xf bank_mask:0xc bound_ctrl:1
	v_pk_fma_f32 v[166:167], v[10:11], v[122:123], v[166:167] op_sel_hi:[1,0,1]
	v_pk_fma_f32 v[164:165], v[12:13], v[122:123], v[164:165] op_sel_hi:[1,0,1]
	ds_read_b128 v[74:77], v124 offset:17152
	ds_read_b128 v[66:69], v124 offset:8960
	ds_read_b128 v[70:73], v124 offset:33536
	ds_read_b128 v[78:81], v124 offset:768
	ds_read_b128 v[62:65], v124 offset:25344
	s_waitcnt lgkmcnt(10)
; #define LAS __attribute__((address_space(3)))
; template <int CTRL> __device__ __forceinline__ float dpp_f(float x) { return __int_as_float(__builtin_amdgcn_update_dpp(0, __float_as_int(x), CTRL, 0xf, 0xf, false)); }
; __device__ __forceinline__ void phase_scan(const Params& p, LAS unsigned char* lds) {
;     ...
;                         for (int u16 = 0; u16 < 16; ++u16) {
;                             const int s = 16 * hb + u16;
;                             const int sn = (s + 1) & 31;
;                             const f32x4 a_n = *(const LAS f32x4*)(sA + sn * 64), w_n = *(const LAS f32x4*)(sW + sn * 64), b_n = *(const LAS f32x4*)(sB + sn * 64);
;                             const f32x4 k_n = *(const LAS f32x4*)(sK + sn * 64), r_n = *(const LAS f32x4*)(sR + sn * 64);
;                             const float v = vq[u16 >> 2][u16 & 3];
;                             const f32x2 vv = {v, v};
;                             f32x2 pp = S01 * (f32x2){a_[0], a_[1]}; pp = S23 * (f32x2){a_[2], a_[3]} + pp;
;                             f32x2 yy = S01 * (f32x2){rp[0], rp[1]}; yy = S23 * (f32x2){rp[2], rp[3]} + yy;
;                             float sa = pp[0] + pp[1], y = yy[0] + yy[1];
;                             sa += dpp_f<0xB1>(sa); y += dpp_f<0xB1>(y);
;                             sa += dpp_f<0x4E>(sa); y += dpp_f<0x4E>(y);
;                             sa += dpp_f<0x141>(sa); y += dpp_f<0x141>(y);
;                             sa += dpp_f<0x140>(sa); y += dpp_f<0x140>(y);
;                             sY[((s - 1) & 31) * 16 + srow] = y;
;                             const f32x2 sv = {sa, sa};
;                             S01 = S01 * (f32x2){w_[0], w_[1]} + vv * (f32x2){k_[0], k_[1]};
;                             S23 = S23 * (f32x2){w_[2], w_[3]} + vv * (f32x2){k_[2], k_[3]};
;                             S01 = sv * (f32x2){b_[0], b_[1]} + S01;
;                             S23 = sv * (f32x2){b_[2], b_[3]} + S23;
;                             rp = r_;
;                             a_ = a_n; w_ = w_n; b_ = b_n; k_ = k_n; r_ = r_n;
;                         }
	v_pk_mul_f32 v[114:115], v[166:167], v[22:23]
	v_pk_fma_f32 v[114:115], v[164:165], v[24:25], v[114:115]
	v_add_f32_e32 v122, v114, v115
	v_pk_mul_f32 v[116:117], v[166:167], v[18:19]
	v_pk_mul_f32 v[118:119], v[82:83], v[34:35] op_sel:[1,0]
	v_add_f32_dpp v122, v122, v122 quad_perm:[1,0,3,2] row_mask:0xf bank_mask:0xf bound_ctrl:1
	v_pk_fma_f32 v[116:117], v[164:165], v[20:21], v[116:117]
	v_pk_mul_f32 v[120:121], v[82:83], v[36:37] op_sel:[1,0]
	v_add_f32_dpp v122, v122, v122 quad_perm:[2,3,0,1] row_mask:0xf bank_mask:0xf bound_ctrl:1
	v_add_f32_e32 v218, v116, v117
	v_pk_fma_f32 v[166:167], v[166:167], v[26:27], v[118:119]
	v_add_f32_dpp v122, v122, v122 row_half_mirror row_mask:0xf bank_mask:0xf bound_ctrl:1
	v_pk_fma_f32 v[164:165], v[164:165], v[28:29], v[120:121]
	v_add_f32_dpp v210, v210, v210 row_mirror row_mask:0xf bank_mask:0xf bound_ctrl:1
	v_add_f32_dpp v122, v122, v122 row_mirror row_mask:0xf bank_mask:0xf bound_ctrl:1
	v_add_f32_dpp v210, v218, v218 row_mirror row_mask:0xf bank_mask:0xc bound_ctrl:1
	v_pk_fma_f32 v[166:167], v[30:31], v[122:123], v[166:167] op_sel_hi:[1,0,1]
	v_pk_fma_f32 v[164:165], v[32:33], v[122:123], v[164:165] op_sel_hi:[1,0,1]
	ds_read_b128 v[14:17], v124 offset:17408
	ds_read_b128 v[6:9], v124 offset:9216
	ds_read_b128 v[10:13], v124 offset:33792
	ds_read_b128 v[18:21], v124 offset:1024
	ds_read_b128 v[2:5], v124 offset:25600
	ds_read_b128 v[86:89], v125 offset:40976
	s_waitcnt lgkmcnt(11)
	v_pk_mul_f32 v[114:115], v[166:167], v[42:43]
	v_pk_fma_f32 v[114:115], v[164:165], v[44:45], v[114:115]
	v_add_f32_e32 v122, v114, v115
	v_pk_mul_f32 v[116:117], v[166:167], v[38:39]
	v_pk_mul_f32 v[118:119], v[84:85], v[54:55] op_sel_hi:[0,1]
	v_add_f32_dpp v122, v122, v122 quad_perm:[1,0,3,2] row_mask:0xf bank_mask:0xf bound_ctrl:1
	v_pk_fma_f32 v[116:117], v[164:165], v[40:41], v[116:117]
	v_pk_mul_f32 v[120:121], v[84:85], v[56:57] op_sel_hi:[0,1]
	v_add_f32_dpp v122, v122, v122 quad_perm:[2,3,0,1] row_mask:0xf bank_mask:0xf bound_ctrl:1
	v_add_f32_e32 v219, v116, v117
	v_pk_fma_f32 v[166:167], v[166:167], v[46:47], v[118:119]
	v_add_f32_dpp v122, v122, v122 row_half_mirror row_mask:0xf bank_mask:0xf bound_ctrl:1
	v_pk_fma_f32 v[164:165], v[164:165], v[48:49], v[120:121]
	v_add_f32_dpp v211, v211, v211 row_mirror row_mask:0xf bank_mask:0xf bound_ctrl:1
	v_add_f32_dpp v122, v122, v122 row_mirror row_mask:0xf bank_mask:0xf bound_ctrl:1
	v_add_f32_dpp v211, v219, v219 row_mirror row_mask:0xf bank_mask:0xc bound_ctrl:1
	v_pk_fma_f32 v[166:167], v[50:51], v[122:123], v[166:167] op_sel_hi:[1,0,1]
	v_pk_fma_f32 v[164:165], v[52:53], v[122:123], v[164:165] op_sel_hi:[1,0,1]
	ds_read_b128 v[34:37], v124 offset:17664
	ds_read_b128 v[26:29], v124 offset:9472
	ds_read_b128 v[30:33], v124 offset:34048
	ds_read_b128 v[38:41], v124 offset:1280
	ds_read_b128 v[22:25], v124 offset:25856
	v_add_f32_dpp v204, v204, v204 row_half_mirror row_mask:0xf bank_mask:0xf bound_ctrl:1
	v_add_f32_dpp v205, v205, v205 row_half_mirror row_mask:0xf bank_mask:0xf bound_ctrl:1
	s_waitcnt lgkmcnt(11)
	v_pk_mul_f32 v[114:115], v[166:167], v[62:63]
	v_pk_fma_f32 v[114:115], v[164:165], v[64:65], v[114:115]
	v_add_f32_e32 v122, v114, v115
	v_pk_mul_f32 v[116:117], v[166:167], v[58:59]
	v_pk_mul_f32 v[118:119], v[84:85], v[74:75] op_sel:[1,0]
	v_add_f32_dpp v122, v122, v122 quad_perm:[1,0,3,2] row_mask:0xf bank_mask:0xf bound_ctrl:1
	v_pk_fma_f32 v[116:117], v[164:165], v[60:61], v[116:117]
	v_pk_mul_f32 v[120:121], v[84:85], v[76:77] op_sel:[1,0]
	v_add_f32_dpp v122, v122, v122 quad_perm:[2,3,0,1] row_mask:0xf bank_mask:0xf bound_ctrl:1
	v_add_f32_e32 v220, v116, v117
	v_pk_fma_f32 v[166:167], v[166:167], v[66:67], v[118:119]
	v_add_f32_dpp v122, v122, v122 row_half_mirror row_mask:0xf bank_mask:0xf bound_ctrl:1
	v_pk_fma_f32 v[164:165], v[164:165], v[68:69], v[120:121]
	v_add_f32_dpp v206, v206, v206 row_half_mirror row_mask:0xf bank_mask:0xf bound_ctrl:1
	v_add_f32_dpp v122, v122, v122 row_mirror row_mask:0xf bank_mask:0xf bound_ctrl:1
	v_add_f32_dpp v207, v207, v207 row_half_mirror row_mask:0xf bank_mask:0xf bound_ctrl:1
	v_pk_fma_f32 v[166:167], v[70:71], v[122:123], v[166:167] op_sel_hi:[1,0,1]
	v_pk_fma_f32 v[164:165], v[72:73], v[122:123], v[164:165] op_sel_hi:[1,0,1]
	ds_read_b128 v[54:57], v124 offset:17920
	ds_read_b128 v[46:49], v124 offset:9728
	ds_read_b128 v[50:53], v124 offset:34304
	ds_read_b128 v[58:61], v124 offset:1536
	ds_read_b128 v[42:45], v124 offset:26112
	v_add_f32_dpp v204, v208, v208 row_half_mirror row_mask:0xf bank_mask:0xa bound_ctrl:1
	v_add_f32_dpp v205, v209, v209 row_half_mirror row_mask:0xf bank_mask:0xa bound_ctrl:1
	s_waitcnt lgkmcnt(11)
	v_pk_mul_f32 v[114:115], v[166:167], v[2:3]
	v_pk_fma_f32 v[114:115], v[164:165], v[4:5], v[114:115]
	v_add_f32_e32 v122, v114, v115
	v_pk_mul_f32 v[116:117], v[166:167], v[78:79]
	s_waitcnt lgkmcnt(10)
	v_pk_mul_f32 v[118:119], v[86:87], v[14:15] op_sel_hi:[0,1]
	v_add_f32_dpp v122, v122, v122 quad_perm:[1,0,3,2] row_mask:0xf bank_mask:0xf bound_ctrl:1
	v_pk_fma_f32 v[116:117], v[164:165], v[80:81], v[116:117]
	v_pk_mul_f32 v[120:121], v[86:87], v[16:17] op_sel_hi:[0,1]
	v_add_f32_dpp v122, v122, v122 quad_perm:[2,3,0,1] row_mask:0xf bank_mask:0xf bound_ctrl:1
	v_add_f32_e32 v221, v116, v117
	v_pk_fma_f32 v[166:167], v[166:167], v[6:7], v[118:119]
	v_add_f32_dpp v122, v122, v122 row_half_mirror row_mask:0xf bank_mask:0xf bound_ctrl:1
	v_pk_fma_f32 v[164:165], v[164:165], v[8:9], v[120:121]
	v_add_f32_dpp v206, v210, v210 row_half_mirror row_mask:0xf bank_mask:0xa bound_ctrl:1
	v_add_f32_dpp v122, v122, v122 row_mirror row_mask:0xf bank_mask:0xf bound_ctrl:1
	v_add_f32_dpp v207, v211, v211 row_half_mirror row_mask:0xf bank_mask:0xa bound_ctrl:1
	v_pk_fma_f32 v[166:167], v[10:11], v[122:123], v[166:167] op_sel_hi:[1,0,1]
	v_pk_fma_f32 v[164:165], v[12:13], v[122:123], v[164:165] op_sel_hi:[1,0,1]
	ds_read_b128 v[74:77], v124 offset:18176
	ds_read_b128 v[66:69], v124 offset:9984
	ds_read_b128 v[70:73], v124 offset:34560
	ds_read_b128 v[78:81], v124 offset:1792
	ds_read_b128 v[62:65], v124 offset:26368
	v_add_f32_dpp v204, v204, v204 quad_perm:[1,0,3,2] row_mask:0xf bank_mask:0xf bound_ctrl:1
	v_add_f32_dpp v205, v205, v205 quad_perm:[1,0,3,2] row_mask:0xf bank_mask:0xf bound_ctrl:1
	s_waitcnt lgkmcnt(10)
; #define LAS __attribute__((address_space(3)))
; template <int CTRL> __device__ __forceinline__ float dpp_f(float x) { return __int_as_float(__builtin_amdgcn_update_dpp(0, __float_as_int(x), CTRL, 0xf, 0xf, false)); }
; __device__ __forceinline__ void phase_scan(const Params& p, LAS unsigned char* lds) {
;     ...
;                         for (int u16 = 0; u16 < 16; ++u16) {
;                             const int s = 16 * hb + u16;
;                             const int sn = (s + 1) & 31;
;                             const f32x4 a_n = *(const LAS f32x4*)(sA + sn * 64), w_n = *(const LAS f32x4*)(sW + sn * 64), b_n = *(const LAS f32x4*)(sB + sn * 64);
;                             const f32x4 k_n = *(const LAS f32x4*)(sK + sn * 64), r_n = *(const LAS f32x4*)(sR + sn * 64);
;                             const float v = vq[u16 >> 2][u16 & 3];
;                             const f32x2 vv = {v, v};
;                             f32x2 pp = S01 * (f32x2){a_[0], a_[1]}; pp = S23 * (f32x2){a_[2], a_[3]} + pp;
;                             f32x2 yy = S01 * (f32x2){rp[0], rp[1]}; yy = S23 * (f32x2){rp[2], rp[3]} + yy;
;                             float sa = pp[0] + pp[1], y = yy[0] + yy[1];
;                             sa += dpp_f<0xB1>(sa); y += dpp_f<0xB1>(y);
;                             sa += dpp_f<0x4E>(sa); y += dpp_f<0x4E>(y);
;                             sa += dpp_f<0x141>(sa); y += dpp_f<0x141>(y);
;                             sa += dpp_f<0x140>(sa); y += dpp_f<0x140>(y);
;                             sY[((s - 1) & 31) * 16 + srow] = y;
;                             const f32x2 sv = {sa, sa};
;                             S01 = S01 * (f32x2){w_[0], w_[1]} + vv * (f32x2){k_[0], k_[1]};
;                             S23 = S23 * (f32x2){w_[2], w_[3]} + vv * (f32x2){k_[2], k_[3]};
;                             S01 = sv * (f32x2){b_[0], b_[1]} + S01;
;                             S23 = sv * (f32x2){b_[2], b_[3]} + S23;
;                             rp = r_;
;                             a_ = a_n; w_ = w_n; b_ = b_n; k_ = k_n; r_ = r_n;
;                         }
	v_pk_mul_f32 v[114:115], v[166:167], v[22:23]
	v_pk_fma_f32 v[114:115], v[164:165], v[24:25], v[114:115]
	v_add_f32_e32 v122, v114, v115
	v_pk_mul_f32 v[116:117], v[166:167], v[18:19]
	v_pk_mul_f32 v[118:119], v[86:87], v[34:35] op_sel:[1,0]
	v_add_f32_dpp v122, v122, v122 quad_perm:[1,0,3,2] row_mask:0xf bank_mask:0xf bound_ctrl:1
	v_pk_fma_f32 v[116:117], v[164:165], v[20:21], v[116:117]
	v_pk_mul_f32 v[120:121], v[86:87], v[36:37] op_sel:[1,0]
	v_add_f32_dpp v122, v122, v122 quad_perm:[2,3,0,1] row_mask:0xf bank_mask:0xf bound_ctrl:1
	v_add_f32_e32 v222, v116, v117
	v_pk_fma_f32 v[166:167], v[166:167], v[26:27], v[118:119]
	v_add_f32_dpp v122, v122, v122 row_half_mirror row_mask:0xf bank_mask:0xf bound_ctrl:1
	v_pk_fma_f32 v[164:165], v[164:165], v[28:29], v[120:121]
	v_add_f32_dpp v206, v206, v206 quad_perm:[1,0,3,2] row_mask:0xf bank_mask:0xf bound_ctrl:1
	v_add_f32_dpp v122, v122, v122 row_mirror row_mask:0xf bank_mask:0xf bound_ctrl:1
	v_add_f32_dpp v207, v207, v207 quad_perm:[1,0,3,2] row_mask:0xf bank_mask:0xf bound_ctrl:1
	v_pk_fma_f32 v[166:167], v[30:31], v[122:123], v[166:167] op_sel_hi:[1,0,1]
	v_pk_fma_f32 v[164:165], v[32:33], v[122:123], v[164:165] op_sel_hi:[1,0,1]
	ds_read_b128 v[14:17], v124 offset:18432
	ds_read_b128 v[6:9], v124 offset:10240
	ds_read_b128 v[10:13], v124 offset:34816
	ds_read_b128 v[18:21], v124 offset:2048
	ds_read_b128 v[2:5], v124 offset:26624
	ds_read_b128 v[90:93], v125 offset:40992
	v_add_f32_dpp v204, v204, v204 quad_perm:[2,3,0,1] row_mask:0xf bank_mask:0xf bound_ctrl:1
	v_add_f32_dpp v205, v205, v205 quad_perm:[2,3,0,1] row_mask:0xf bank_mask:0xf bound_ctrl:1
	s_waitcnt lgkmcnt(11)
	v_pk_mul_f32 v[114:115], v[166:167], v[42:43]
	v_pk_fma_f32 v[114:115], v[164:165], v[44:45], v[114:115]
	v_add_f32_e32 v122, v114, v115
	v_pk_mul_f32 v[116:117], v[166:167], v[38:39]
	v_pk_mul_f32 v[118:119], v[88:89], v[54:55] op_sel_hi:[0,1]
	v_add_f32_dpp v122, v122, v122 quad_perm:[1,0,3,2] row_mask:0xf bank_mask:0xf bound_ctrl:1
	v_pk_fma_f32 v[116:117], v[164:165], v[40:41], v[116:117]
	v_pk_mul_f32 v[120:121], v[88:89], v[56:57] op_sel_hi:[0,1]
	v_add_f32_dpp v122, v122, v122 quad_perm:[2,3,0,1] row_mask:0xf bank_mask:0xf bound_ctrl:1
	v_add_f32_e32 v223, v116, v117
	v_pk_fma_f32 v[166:167], v[166:167], v[46:47], v[118:119]
	v_add_f32_dpp v122, v122, v122 row_half_mirror row_mask:0xf bank_mask:0xf bound_ctrl:1
	v_pk_fma_f32 v[164:165], v[164:165], v[48:49], v[120:121]
	v_add_f32_dpp v206, v206, v206 quad_perm:[2,3,0,1] row_mask:0xf bank_mask:0xf bound_ctrl:1
	v_add_f32_dpp v122, v122, v122 row_mirror row_mask:0xf bank_mask:0xf bound_ctrl:1
	v_add_f32_dpp v207, v207, v207 quad_perm:[2,3,0,1] row_mask:0xf bank_mask:0xf bound_ctrl:1
	v_pk_fma_f32 v[166:167], v[50:51], v[122:123], v[166:167] op_sel_hi:[1,0,1]
	v_pk_fma_f32 v[164:165], v[52:53], v[122:123], v[164:165] op_sel_hi:[1,0,1]
	ds_read_b128 v[34:37], v124 offset:18688
	ds_read_b128 v[26:29], v124 offset:10496
	ds_read_b128 v[30:33], v124 offset:35072
	ds_read_b128 v[38:41], v124 offset:2304
	ds_read_b128 v[22:25], v124 offset:26880
	v_cndmask_b32_e64 v202, v204, v205, s[34:35]
	v_cndmask_b32_e64 v202, v202, v206, s[56:57]
	s_waitcnt lgkmcnt(11)
	v_pk_mul_f32 v[114:115], v[166:167], v[62:63]
	v_pk_fma_f32 v[114:115], v[164:165], v[64:65], v[114:115]
	v_add_f32_e32 v122, v114, v115
	v_pk_mul_f32 v[116:117], v[166:167], v[58:59]
	v_pk_mul_f32 v[118:119], v[88:89], v[74:75] op_sel:[1,0]
	v_add_f32_dpp v122, v122, v122 quad_perm:[1,0,3,2] row_mask:0xf bank_mask:0xf bound_ctrl:1
	v_pk_fma_f32 v[116:117], v[164:165], v[60:61], v[116:117]
	v_pk_mul_f32 v[120:121], v[88:89], v[76:77] op_sel:[1,0]
	v_add_f32_dpp v122, v122, v122 quad_perm:[2,3,0,1] row_mask:0xf bank_mask:0xf bound_ctrl:1
	v_add_f32_e32 v224, v116, v117
	v_pk_fma_f32 v[166:167], v[166:167], v[66:67], v[118:119]
	v_add_f32_dpp v122, v122, v122 row_half_mirror row_mask:0xf bank_mask:0xf bound_ctrl:1
	v_pk_fma_f32 v[164:165], v[164:165], v[68:69], v[120:121]
	v_cndmask_b32_e64 v202, v202, v207, s[98:99]
	v_add_f32_dpp v122, v122, v122 row_mirror row_mask:0xf bank_mask:0xf bound_ctrl:1
	v_cvt_f16_f32_e32 v203, v202
	v_pk_fma_f32 v[166:167], v[70:71], v[122:123], v[166:167] op_sel_hi:[1,0,1]
	v_pk_fma_f32 v[164:165], v[72:73], v[122:123], v[164:165] op_sel_hi:[1,0,1]
	ds_read_b128 v[54:57], v124 offset:18944
	ds_read_b128 v[46:49], v124 offset:10752
	ds_read_b128 v[50:53], v124 offset:35328
	ds_read_b128 v[58:61], v124 offset:2560
	ds_read_b128 v[42:45], v124 offset:27136
	s_mov_b64 exec, s[14:15]
	global_store_short v[128:129], v203, off
	s_mov_b64 exec, -1
	v_lshl_add_u64 v[128:129], v[128:129], 0, s[100:101]
	s_waitcnt lgkmcnt(11)
	v_pk_mul_f32 v[114:115], v[166:167], v[2:3]
	v_pk_fma_f32 v[114:115], v[164:165], v[4:5], v[114:115]
	v_add_f32_e32 v122, v114, v115
	v_pk_mul_f32 v[116:117], v[166:167], v[78:79]
	s_waitcnt lgkmcnt(10)
	v_pk_mul_f32 v[118:119], v[90:91], v[14:15] op_sel_hi:[0,1]
	v_add_f32_dpp v122, v122, v122 quad_perm:[1,0,3,2] row_mask:0xf bank_mask:0xf bound_ctrl:1
	v_pk_fma_f32 v[116:117], v[164:165], v[80:81], v[116:117]
	v_pk_mul_f32 v[120:121], v[90:91], v[16:17] op_sel_hi:[0,1]
	v_add_f32_dpp v122, v122, v122 quad_perm:[2,3,0,1] row_mask:0xf bank_mask:0xf bound_ctrl:1
	v_add_f32_e32 v225, v116, v117
	v_pk_fma_f32 v[166:167], v[166:167], v[6:7], v[118:119]
	v_add_f32_dpp v122, v122, v122 row_half_mirror row_mask:0xf bank_mask:0xf bound_ctrl:1
	v_pk_fma_f32 v[164:165], v[164:165], v[8:9], v[120:121]
	s_nop 0
	v_add_f32_dpp v122, v122, v122 row_mirror row_mask:0xf bank_mask:0xf bound_ctrl:1
	v_pk_fma_f32 v[166:167], v[10:11], v[122:123], v[166:167] op_sel_hi:[1,0,1]
	v_pk_fma_f32 v[164:165], v[12:13], v[122:123], v[164:165] op_sel_hi:[1,0,1]
	ds_read_b128 v[74:77], v124 offset:19200
	ds_read_b128 v[66:69], v124 offset:11008
	ds_read_b128 v[70:73], v124 offset:35584
	ds_read_b128 v[78:81], v124 offset:2816
	ds_read_b128 v[62:65], v124 offset:27392
	s_waitcnt lgkmcnt(10)
; #define LAS __attribute__((address_space(3)))
; template <int CTRL> __device__ __forceinline__ float dpp_f(float x) { return __int_as_float(__builtin_amdgcn_update_dpp(0, __float_as_int(x), CTRL, 0xf, 0xf, false)); }
; __device__ __forceinline__ void phase_scan(const Params& p, LAS unsigned char* lds) {
;     ...
;                         for (int u16 = 0; u16 < 16; ++u16) {
;                             const int s = 16 * hb + u16;
;                             const int sn = (s + 1) & 31;
;                             const f32x4 a_n = *(const LAS f32x4*)(sA + sn * 64), w_n = *(const LAS f32x4*)(sW + sn * 64), b_n = *(const LAS f32x4*)(sB + sn * 64);
;                             const f32x4 k_n = *(const LAS f32x4*)(sK + sn * 64), r_n = *(const LAS f32x4*)(sR + sn * 64);
;                             const float v = vq[u16 >> 2][u16 & 3];
;                             const f32x2 vv = {v, v};
;                             f32x2 pp = S01 * (f32x2){a_[0], a_[1]}; pp = S23 * (f32x2){a_[2], a_[3]} + pp;
;                             f32x2 yy = S01 * (f32x2){rp[0], rp[1]}; yy = S23 * (f32x2){rp[2], rp[3]} + yy;
;                             float sa = pp[0] + pp[1], y = yy[0] + yy[1];
;                             sa += dpp_f<0xB1>(sa); y += dpp_f<0xB1>(y);
;                             sa += dpp_f<0x4E>(sa); y += dpp_f<0x4E>(y);
;                             sa += dpp_f<0x141>(sa); y += dpp_f<0x141>(y);
;                             sa += dpp_f<0x140>(sa); y += dpp_f<0x140>(y);
;                             sY[((s - 1) & 31) * 16 + srow] = y;
;                             const f32x2 sv = {sa, sa};
;                             S01 = S01 * (f32x2){w_[0], w_[1]} + vv * (f32x2){k_[0], k_[1]};
;                             S23 = S23 * (f32x2){w_[2], w_[3]} + vv * (f32x2){k_[2], k_[3]};
;                             S01 = sv * (f32x2){b_[0], b_[1]} + S01;
;                             S23 = sv * (f32x2){b_[2], b_[3]} + S23;
;                             rp = r_;
;                             a_ = a_n; w_ = w_n; b_ = b_n; k_ = k_n; r_ = r_n;
;                         }
	v_pk_mul_f32 v[114:115], v[166:167], v[22:23]
	v_pk_fma_f32 v[114:115], v[164:165], v[24:25], v[114:115]
	v_add_f32_e32 v122, v114, v115
	v_pk_mul_f32 v[116:117], v[166:167], v[18:19]
	v_pk_mul_f32 v[118:119], v[90:91], v[34:35] op_sel:[1,0]
	v_add_f32_dpp v122, v122, v122 quad_perm:[1,0,3,2] row_mask:0xf bank_mask:0xf bound_ctrl:1
	v_pk_fma_f32 v[116:117], v[164:165], v[20:21], v[116:117]
	v_pk_mul_f32 v[120:121], v[90:91], v[36:37] op_sel:[1,0]
	v_add_f32_dpp v122, v122, v122 quad_perm:[2,3,0,1] row_mask:0xf bank_mask:0xf bound_ctrl:1
	v_add_f32_e32 v226, v116, v117
	v_pk_fma_f32 v[166:167], v[166:167], v[26:27], v[118:119]
	v_add_f32_dpp v122, v122, v122 row_half_mirror row_mask:0xf bank_mask:0xf bound_ctrl:1
	v_pk_fma_f32 v[164:165], v[164:165], v[28:29], v[120:121]
	s_nop 0
	v_add_f32_dpp v122, v122, v122 row_mirror row_mask:0xf bank_mask:0xf bound_ctrl:1
	v_pk_fma_f32 v[166:167], v[30:31], v[122:123], v[166:167] op_sel_hi:[1,0,1]
	v_pk_fma_f32 v[164:165], v[32:33], v[122:123], v[164:165] op_sel_hi:[1,0,1]
	ds_read_b128 v[14:17], v124 offset:19456
	ds_read_b128 v[6:9], v124 offset:11264
	ds_read_b128 v[10:13], v124 offset:35840
	ds_read_b128 v[18:21], v124 offset:3072
	ds_read_b128 v[2:5], v124 offset:27648
	ds_read_b128 v[94:97], v125 offset:41008
	s_waitcnt lgkmcnt(11)
	v_pk_mul_f32 v[114:115], v[166:167], v[42:43]
	v_pk_fma_f32 v[114:115], v[164:165], v[44:45], v[114:115]
	v_add_f32_e32 v122, v114, v115
	v_pk_mul_f32 v[116:117], v[166:167], v[38:39]
	v_pk_mul_f32 v[118:119], v[92:93], v[54:55] op_sel_hi:[0,1]
	v_add_f32_dpp v122, v122, v122 quad_perm:[1,0,3,2] row_mask:0xf bank_mask:0xf bound_ctrl:1
	v_pk_fma_f32 v[116:117], v[164:165], v[40:41], v[116:117]
	v_pk_mul_f32 v[120:121], v[92:93], v[56:57] op_sel_hi:[0,1]
	v_add_f32_dpp v122, v122, v122 quad_perm:[2,3,0,1] row_mask:0xf bank_mask:0xf bound_ctrl:1
	v_add_f32_e32 v227, v116, v117
	v_pk_fma_f32 v[166:167], v[166:167], v[46:47], v[118:119]
	v_add_f32_dpp v122, v122, v122 row_half_mirror row_mask:0xf bank_mask:0xf bound_ctrl:1
	v_pk_fma_f32 v[164:165], v[164:165], v[48:49], v[120:121]
	s_nop 0
	v_add_f32_dpp v122, v122, v122 row_mirror row_mask:0xf bank_mask:0xf bound_ctrl:1
	v_pk_fma_f32 v[166:167], v[50:51], v[122:123], v[166:167] op_sel_hi:[1,0,1]
	v_pk_fma_f32 v[164:165], v[52:53], v[122:123], v[164:165] op_sel_hi:[1,0,1]
	ds_read_b128 v[34:37], v124 offset:19712
	ds_read_b128 v[26:29], v124 offset:11520
	ds_read_b128 v[30:33], v124 offset:36096
	ds_read_b128 v[38:41], v124 offset:3328
	ds_read_b128 v[22:25], v124 offset:27904
	s_waitcnt lgkmcnt(11)
	v_pk_mul_f32 v[114:115], v[166:167], v[62:63]
	v_pk_fma_f32 v[114:115], v[164:165], v[64:65], v[114:115]
	v_add_f32_e32 v122, v114, v115
	v_pk_mul_f32 v[116:117], v[166:167], v[58:59]
	v_pk_mul_f32 v[118:119], v[92:93], v[74:75] op_sel:[1,0]
	v_add_f32_dpp v122, v122, v122 quad_perm:[1,0,3,2] row_mask:0xf bank_mask:0xf bound_ctrl:1
	v_pk_fma_f32 v[116:117], v[164:165], v[60:61], v[116:117]
	v_pk_mul_f32 v[120:121], v[92:93], v[76:77] op_sel:[1,0]
	v_add_f32_dpp v122, v122, v122 quad_perm:[2,3,0,1] row_mask:0xf bank_mask:0xf bound_ctrl:1
	v_add_f32_e32 v228, v116, v117
	v_pk_fma_f32 v[166:167], v[166:167], v[66:67], v[118:119]
	v_add_f32_dpp v122, v122, v122 row_half_mirror row_mask:0xf bank_mask:0xf bound_ctrl:1
	v_pk_fma_f32 v[164:165], v[164:165], v[68:69], v[120:121]
	v_add_f32_dpp v220, v220, v220 row_mirror row_mask:0xf bank_mask:0xf bound_ctrl:1
	v_add_f32_dpp v122, v122, v122 row_mirror row_mask:0xf bank_mask:0xf bound_ctrl:1
	v_add_f32_dpp v220, v228, v228 row_mirror row_mask:0xf bank_mask:0xc bound_ctrl:1
	v_pk_fma_f32 v[166:167], v[70:71], v[122:123], v[166:167] op_sel_hi:[1,0,1]
	v_pk_fma_f32 v[164:165], v[72:73], v[122:123], v[164:165] op_sel_hi:[1,0,1]
	ds_read_b128 v[54:57], v124 offset:19968
	ds_read_b128 v[46:49], v124 offset:11776
	ds_read_b128 v[50:53], v124 offset:36352
	ds_read_b128 v[58:61], v124 offset:3584
	ds_read_b128 v[42:45], v124 offset:28160
	s_waitcnt lgkmcnt(11)
	v_pk_mul_f32 v[114:115], v[166:167], v[2:3]
	v_pk_fma_f32 v[114:115], v[164:165], v[4:5], v[114:115]
	v_add_f32_e32 v122, v114, v115
	v_pk_mul_f32 v[116:117], v[166:167], v[78:79]
	s_waitcnt lgkmcnt(10)
	v_pk_mul_f32 v[118:119], v[94:95], v[14:15] op_sel_hi:[0,1]
	v_add_f32_dpp v122, v122, v122 quad_perm:[1,0,3,2] row_mask:0xf bank_mask:0xf bound_ctrl:1
	v_pk_fma_f32 v[116:117], v[164:165], v[80:81], v[116:117]
	v_pk_mul_f32 v[120:121], v[94:95], v[16:17] op_sel_hi:[0,1]
	v_add_f32_dpp v122, v122, v122 quad_perm:[2,3,0,1] row_mask:0xf bank_mask:0xf bound_ctrl:1
	v_add_f32_e32 v229, v116, v117
	v_pk_fma_f32 v[166:167], v[166:167], v[6:7], v[118:119]
	v_add_f32_dpp v122, v122, v122 row_half_mirror row_mask:0xf bank_mask:0xf bound_ctrl:1
	v_pk_fma_f32 v[164:165], v[164:165], v[8:9], v[120:121]
	v_add_f32_dpp v221, v221, v221 row_mirror row_mask:0xf bank_mask:0xf bound_ctrl:1
	v_add_f32_dpp v122, v122, v122 row_mirror row_mask:0xf bank_mask:0xf bound_ctrl:1
	v_add_f32_dpp v221, v229, v229 row_mirror row_mask:0xf bank_mask:0xc bound_ctrl:1
	v_pk_fma_f32 v[166:167], v[10:11], v[122:123], v[166:167] op_sel_hi:[1,0,1]
	v_pk_fma_f32 v[164:165], v[12:13], v[122:123], v[164:165] op_sel_hi:[1,0,1]
	ds_read_b128 v[74:77], v124 offset:20224
	ds_read_b128 v[66:69], v124 offset:12032
	ds_read_b128 v[70:73], v124 offset:36608
	ds_read_b128 v[78:81], v124 offset:3840
	ds_read_b128 v[62:65], v124 offset:28416
	s_waitcnt lgkmcnt(10)
; #define LAS __attribute__((address_space(3)))
; template <int CTRL> __device__ __forceinline__ float dpp_f(float x) { return __int_as_float(__builtin_amdgcn_update_dpp(0, __float_as_int(x), CTRL, 0xf, 0xf, false)); }
; __device__ __forceinline__ void phase_scan(const Params& p, LAS unsigned char* lds) {
;     ...
;                         for (int u16 = 0; u16 < 16; ++u16) {
;                             const int s = 16 * hb + u16;
;                             const int sn = (s + 1) & 31;
;                             const f32x4 a_n = *(const LAS f32x4*)(sA + sn * 64), w_n = *(const LAS f32x4*)(sW + sn * 64), b_n = *(const LAS f32x4*)(sB + sn * 64);
;                             const f32x4 k_n = *(const LAS f32x4*)(sK + sn * 64), r_n = *(const LAS f32x4*)(sR + sn * 64);
;                             const float v = vq[u16 >> 2][u16 & 3];
;                             const f32x2 vv = {v, v};
;                             f32x2 pp = S01 * (f32x2){a_[0], a_[1]}; pp = S23 * (f32x2){a_[2], a_[3]} + pp;
;                             f32x2 yy = S01 * (f32x2){rp[0], rp[1]}; yy = S23 * (f32x2){rp[2], rp[3]} + yy;
;                             float sa = pp[0] + pp[1], y = yy[0] + yy[1];
;                             sa += dpp_f<0xB1>(sa); y += dpp_f<0xB1>(y);
;                             sa += dpp_f<0x4E>(sa); y += dpp_f<0x4E>(y);
;                             sa += dpp_f<0x141>(sa); y += dpp_f<0x141>(y);
;                             sa += dpp_f<0x140>(sa); y += dpp_f<0x140>(y);
;                             sY[((s - 1) & 31) * 16 + srow] = y;
;                             const f32x2 sv = {sa, sa};
;                             S01 = S01 * (f32x2){w_[0], w_[1]} + vv * (f32x2){k_[0], k_[1]};
;                             S23 = S23 * (f32x2){w_[2], w_[3]} + vv * (f32x2){k_[2], k_[3]};
;                             S01 = sv * (f32x2){b_[0], b_[1]} + S01;
;                             S23 = sv * (f32x2){b_[2], b_[3]} + S23;
;                             rp = r_;
;                             a_ = a_n; w_ = w_n; b_ = b_n; k_ = k_n; r_ = r_n;
;                         }
	v_pk_mul_f32 v[114:115], v[166:167], v[22:23]
	v_pk_fma_f32 v[114:115], v[164:165], v[24:25], v[114:115]
	v_add_f32_e32 v122, v114, v115
	v_pk_mul_f32 v[116:117], v[166:167], v[18:19]
	v_pk_mul_f32 v[118:119], v[94:95], v[34:35] op_sel:[1,0]
	v_add_f32_dpp v122, v122, v122 quad_perm:[1,0,3,2] row_mask:0xf bank_mask:0xf bound_ctrl:1
	v_pk_fma_f32 v[116:117], v[164:165], v[20:21], v[116:117]
	v_pk_mul_f32 v[120:121], v[94:95], v[36:37] op_sel:[1,0]
	v_add_f32_dpp v122, v122, v122 quad_perm:[2,3,0,1] row_mask:0xf bank_mask:0xf bound_ctrl:1
	v_add_f32_e32 v230, v116, v117
	v_pk_fma_f32 v[166:167], v[166:167], v[26:27], v[118:119]
	v_add_f32_dpp v122, v122, v122 row_half_mirror row_mask:0xf bank_mask:0xf bound_ctrl:1
	v_pk_fma_f32 v[164:165], v[164:165], v[28:29], v[120:121]
	v_add_f32_dpp v222, v222, v222 row_mirror row_mask:0xf bank_mask:0xf bound_ctrl:1
	v_add_f32_dpp v122, v122, v122 row_mirror row_mask:0xf bank_mask:0xf bound_ctrl:1
	v_add_f32_dpp v222, v230, v230 row_mirror row_mask:0xf bank_mask:0xc bound_ctrl:1
	v_pk_fma_f32 v[166:167], v[30:31], v[122:123], v[166:167] op_sel_hi:[1,0,1]
	v_pk_fma_f32 v[164:165], v[32:33], v[122:123], v[164:165] op_sel_hi:[1,0,1]
	ds_read_b128 v[14:17], v124 offset:20480
	ds_read_b128 v[6:9], v124 offset:12288
	ds_read_b128 v[10:13], v124 offset:36864
	ds_read_b128 v[18:21], v124 offset:4096
	ds_read_b128 v[2:5], v124 offset:28672
	ds_read_b128 v[98:101], v125 offset:41024
	s_waitcnt lgkmcnt(11)
	v_pk_mul_f32 v[114:115], v[166:167], v[42:43]
	v_pk_fma_f32 v[114:115], v[164:165], v[44:45], v[114:115]
	v_add_f32_e32 v122, v114, v115
	v_pk_mul_f32 v[116:117], v[166:167], v[38:39]
	v_pk_mul_f32 v[118:119], v[96:97], v[54:55] op_sel_hi:[0,1]
	v_add_f32_dpp v122, v122, v122 quad_perm:[1,0,3,2] row_mask:0xf bank_mask:0xf bound_ctrl:1
	v_pk_fma_f32 v[116:117], v[164:165], v[40:41], v[116:117]
	v_pk_mul_f32 v[120:121], v[96:97], v[56:57] op_sel_hi:[0,1]
	v_add_f32_dpp v122, v122, v122 quad_perm:[2,3,0,1] row_mask:0xf bank_mask:0xf bound_ctrl:1
	v_add_f32_e32 v231, v116, v117
	v_pk_fma_f32 v[166:167], v[166:167], v[46:47], v[118:119]
	v_add_f32_dpp v122, v122, v122 row_half_mirror row_mask:0xf bank_mask:0xf bound_ctrl:1
	v_pk_fma_f32 v[164:165], v[164:165], v[48:49], v[120:121]
	v_add_f32_dpp v223, v223, v223 row_mirror row_mask:0xf bank_mask:0xf bound_ctrl:1
	v_add_f32_dpp v122, v122, v122 row_mirror row_mask:0xf bank_mask:0xf bound_ctrl:1
	v_add_f32_dpp v223, v231, v231 row_mirror row_mask:0xf bank_mask:0xc bound_ctrl:1
	v_pk_fma_f32 v[166:167], v[50:51], v[122:123], v[166:167] op_sel_hi:[1,0,1]
	v_pk_fma_f32 v[164:165], v[52:53], v[122:123], v[164:165] op_sel_hi:[1,0,1]
	ds_read_b128 v[34:37], v124 offset:20736
	ds_read_b128 v[26:29], v124 offset:12544
	ds_read_b128 v[30:33], v124 offset:37120
	ds_read_b128 v[38:41], v124 offset:4352
	ds_read_b128 v[22:25], v124 offset:28928
	s_waitcnt lgkmcnt(11)
	v_pk_mul_f32 v[114:115], v[166:167], v[62:63]
	v_pk_fma_f32 v[114:115], v[164:165], v[64:65], v[114:115]
	v_add_f32_e32 v122, v114, v115
	v_pk_mul_f32 v[116:117], v[166:167], v[58:59]
	v_pk_mul_f32 v[118:119], v[96:97], v[74:75] op_sel:[1,0]
	v_add_f32_dpp v122, v122, v122 quad_perm:[1,0,3,2] row_mask:0xf bank_mask:0xf bound_ctrl:1
	v_pk_fma_f32 v[116:117], v[164:165], v[60:61], v[116:117]
	v_pk_mul_f32 v[120:121], v[96:97], v[76:77] op_sel:[1,0]
	v_add_f32_dpp v122, v122, v122 quad_perm:[2,3,0,1] row_mask:0xf bank_mask:0xf bound_ctrl:1
	v_add_f32_e32 v232, v116, v117
	v_pk_fma_f32 v[166:167], v[166:167], v[66:67], v[118:119]
	v_add_f32_dpp v122, v122, v122 row_half_mirror row_mask:0xf bank_mask:0xf bound_ctrl:1
	v_pk_fma_f32 v[164:165], v[164:165], v[68:69], v[120:121]
	v_add_f32_dpp v224, v224, v224 row_mirror row_mask:0xf bank_mask:0xf bound_ctrl:1
	v_add_f32_dpp v122, v122, v122 row_mirror row_mask:0xf bank_mask:0xf bound_ctrl:1
	v_add_f32_dpp v224, v232, v232 row_mirror row_mask:0xf bank_mask:0xc bound_ctrl:1
	v_pk_fma_f32 v[166:167], v[70:71], v[122:123], v[166:167] op_sel_hi:[1,0,1]
	v_pk_fma_f32 v[164:165], v[72:73], v[122:123], v[164:165] op_sel_hi:[1,0,1]
	ds_read_b128 v[54:57], v124 offset:20992
	ds_read_b128 v[46:49], v124 offset:12800
	ds_read_b128 v[50:53], v124 offset:37376
	ds_read_b128 v[58:61], v124 offset:4608
	ds_read_b128 v[42:45], v124 offset:29184
	s_waitcnt lgkmcnt(11)
	v_pk_mul_f32 v[114:115], v[166:167], v[2:3]
	v_pk_fma_f32 v[114:115], v[164:165], v[4:5], v[114:115]
	v_add_f32_e32 v122, v114, v115
	v_pk_mul_f32 v[116:117], v[166:167], v[78:79]
	s_waitcnt lgkmcnt(10)
	v_pk_mul_f32 v[118:119], v[98:99], v[14:15] op_sel_hi:[0,1]
	v_add_f32_dpp v122, v122, v122 quad_perm:[1,0,3,2] row_mask:0xf bank_mask:0xf bound_ctrl:1
	v_pk_fma_f32 v[116:117], v[164:165], v[80:81], v[116:117]
	v_pk_mul_f32 v[120:121], v[98:99], v[16:17] op_sel_hi:[0,1]
	v_add_f32_dpp v122, v122, v122 quad_perm:[2,3,0,1] row_mask:0xf bank_mask:0xf bound_ctrl:1
	v_add_f32_e32 v233, v116, v117
	v_pk_fma_f32 v[166:167], v[166:167], v[6:7], v[118:119]
	v_add_f32_dpp v122, v122, v122 row_half_mirror row_mask:0xf bank_mask:0xf bound_ctrl:1
	v_pk_fma_f32 v[164:165], v[164:165], v[8:9], v[120:121]
	v_add_f32_dpp v225, v225, v225 row_mirror row_mask:0xf bank_mask:0xf bound_ctrl:1
	v_add_f32_dpp v122, v122, v122 row_mirror row_mask:0xf bank_mask:0xf bound_ctrl:1
	v_add_f32_dpp v225, v233, v233 row_mirror row_mask:0xf bank_mask:0xc bound_ctrl:1
	v_pk_fma_f32 v[166:167], v[10:11], v[122:123], v[166:167] op_sel_hi:[1,0,1]
	v_pk_fma_f32 v[164:165], v[12:13], v[122:123], v[164:165] op_sel_hi:[1,0,1]
	ds_read_b128 v[74:77], v124 offset:21248
	ds_read_b128 v[66:69], v124 offset:13056
	ds_read_b128 v[70:73], v124 offset:37632
	ds_read_b128 v[78:81], v124 offset:4864
	ds_read_b128 v[62:65], v124 offset:29440
	s_waitcnt lgkmcnt(10)
; #define LAS __attribute__((address_space(3)))
; __device__ __forceinline__ void phase_scan(const Params& p, LAS unsigned char* lds) {
;     ...
;                     for (int hb = 0; hb < 2; ++hb) {
;                         f32x4 vn[4];
; #pragma unroll
;                         for (int u = 0; u < 4; ++u) vn[u] = *(const LAS f32x4*)(sV + srow * 32 + ((16 * (hb + 1)) & 31) + 4 * u);
; #pragma unroll
;                         for (int u16 = 0; u16 < 16; ++u16) {
;                             const int s = 16 * hb + u16;
;                             const int sn = (s + 1) & 31;
;                             const f32x4 a_n = *(const LAS f32x4*)(sA + sn * 64), w_n = *(const LAS f32x4*)(sW + sn * 64), b_n = *(const LAS f32x4*)(sB + sn * 64);
;                             const f32x4 k_n = *(const LAS f32x4*)(sK + sn * 64), r_n = *(const LAS f32x4*)(sR + sn * 64);
;                             const float v = vq[u16 >> 2][u16 & 3];
;                             const f32x2 vv = {v, v};
;                             f32x2 pp = S01 * (f32x2){a_[0], a_[1]}; pp = S23 * (f32x2){a_[2], a_[3]} + pp;
;                             f32x2 yy = S01 * (f32x2){rp[0], rp[1]}; yy = S23 * (f32x2){rp[2], rp[3]} + yy;
;                             float sa = pp[0] + pp[1], y = yy[0] + yy[1];
;                             sa += dpp_f<0xB1>(sa); y += dpp_f<0xB1>(y);
;                             sa += dpp_f<0x4E>(sa); y += dpp_f<0x4E>(y);
;                             sa += dpp_f<0x141>(sa); y += dpp_f<0x141>(y);
;                             sa += dpp_f<0x140>(sa); y += dpp_f<0x140>(y);
;                             sY[((s - 1) & 31) * 16 + srow] = y;
;                             const f32x2 sv = {sa, sa};
;                             S01 = S01 * (f32x2){w_[0], w_[1]} + vv * (f32x2){k_[0], k_[1]};
;                             S23 = S23 * (f32x2){w_[2], w_[3]} + vv * (f32x2){k_[2], k_[3]};
;                             S01 = sv * (f32x2){b_[0], b_[1]} + S01;
;                             S23 = sv * (f32x2){b_[2], b_[3]} + S23;
;                             rp = r_;
;                             a_ = a_n; w_ = w_n; b_ = b_n; k_ = k_n; r_ = r_n;
;                         }
; #pragma unroll
;                         for (int u = 0; u < 4; ++u) vq[u] = vn[u];
	v_pk_mul_f32 v[114:115], v[166:167], v[22:23]
	v_pk_fma_f32 v[114:115], v[164:165], v[24:25], v[114:115]
	v_add_f32_e32 v122, v114, v115
	v_pk_mul_f32 v[116:117], v[166:167], v[18:19]
	v_pk_mul_f32 v[118:119], v[98:99], v[34:35] op_sel:[1,0]
	v_add_f32_dpp v122, v122, v122 quad_perm:[1,0,3,2] row_mask:0xf bank_mask:0xf bound_ctrl:1
	v_pk_fma_f32 v[116:117], v[164:165], v[20:21], v[116:117]
	v_pk_mul_f32 v[120:121], v[98:99], v[36:37] op_sel:[1,0]
	v_add_f32_dpp v122, v122, v122 quad_perm:[2,3,0,1] row_mask:0xf bank_mask:0xf bound_ctrl:1
	v_add_f32_e32 v234, v116, v117
	v_pk_fma_f32 v[166:167], v[166:167], v[26:27], v[118:119]
	v_add_f32_dpp v122, v122, v122 row_half_mirror row_mask:0xf bank_mask:0xf bound_ctrl:1
	v_pk_fma_f32 v[164:165], v[164:165], v[28:29], v[120:121]
	v_add_f32_dpp v226, v226, v226 row_mirror row_mask:0xf bank_mask:0xf bound_ctrl:1
	v_add_f32_dpp v122, v122, v122 row_mirror row_mask:0xf bank_mask:0xf bound_ctrl:1
	v_add_f32_dpp v226, v234, v234 row_mirror row_mask:0xf bank_mask:0xc bound_ctrl:1
	v_pk_fma_f32 v[166:167], v[30:31], v[122:123], v[166:167] op_sel_hi:[1,0,1]
	v_pk_fma_f32 v[164:165], v[32:33], v[122:123], v[164:165] op_sel_hi:[1,0,1]
	ds_read_b128 v[14:17], v124 offset:21504
	ds_read_b128 v[6:9], v124 offset:13312
	ds_read_b128 v[10:13], v124 offset:37888
	ds_read_b128 v[18:21], v124 offset:5120
	ds_read_b128 v[2:5], v124 offset:29696
	ds_read_b128 v[102:105], v125 offset:41040
	s_waitcnt lgkmcnt(11)
	v_pk_mul_f32 v[114:115], v[166:167], v[42:43]
	v_pk_fma_f32 v[114:115], v[164:165], v[44:45], v[114:115]
	v_add_f32_e32 v122, v114, v115
	v_pk_mul_f32 v[116:117], v[166:167], v[38:39]
	v_pk_mul_f32 v[118:119], v[100:101], v[54:55] op_sel_hi:[0,1]
	v_add_f32_dpp v122, v122, v122 quad_perm:[1,0,3,2] row_mask:0xf bank_mask:0xf bound_ctrl:1
	v_pk_fma_f32 v[116:117], v[164:165], v[40:41], v[116:117]
	v_pk_mul_f32 v[120:121], v[100:101], v[56:57] op_sel_hi:[0,1]
	v_add_f32_dpp v122, v122, v122 quad_perm:[2,3,0,1] row_mask:0xf bank_mask:0xf bound_ctrl:1
	v_add_f32_e32 v235, v116, v117
	v_pk_fma_f32 v[166:167], v[166:167], v[46:47], v[118:119]
	v_add_f32_dpp v122, v122, v122 row_half_mirror row_mask:0xf bank_mask:0xf bound_ctrl:1
	v_pk_fma_f32 v[164:165], v[164:165], v[48:49], v[120:121]
	v_add_f32_dpp v227, v227, v227 row_mirror row_mask:0xf bank_mask:0xf bound_ctrl:1
	v_add_f32_dpp v122, v122, v122 row_mirror row_mask:0xf bank_mask:0xf bound_ctrl:1
	v_add_f32_dpp v227, v235, v235 row_mirror row_mask:0xf bank_mask:0xc bound_ctrl:1
	v_pk_fma_f32 v[166:167], v[50:51], v[122:123], v[166:167] op_sel_hi:[1,0,1]
	v_pk_fma_f32 v[164:165], v[52:53], v[122:123], v[164:165] op_sel_hi:[1,0,1]
	ds_read_b128 v[34:37], v124 offset:21760
	ds_read_b128 v[26:29], v124 offset:13568
	ds_read_b128 v[30:33], v124 offset:38144
	ds_read_b128 v[38:41], v124 offset:5376
	ds_read_b128 v[22:25], v124 offset:29952
	v_add_f32_dpp v220, v220, v220 row_half_mirror row_mask:0xf bank_mask:0xf bound_ctrl:1
	v_add_f32_dpp v221, v221, v221 row_half_mirror row_mask:0xf bank_mask:0xf bound_ctrl:1
	s_waitcnt lgkmcnt(11)
	v_pk_mul_f32 v[114:115], v[166:167], v[62:63]
	v_pk_fma_f32 v[114:115], v[164:165], v[64:65], v[114:115]
	v_add_f32_e32 v122, v114, v115
	v_pk_mul_f32 v[116:117], v[166:167], v[58:59]
	v_pk_mul_f32 v[118:119], v[100:101], v[74:75] op_sel:[1,0]
	v_add_f32_dpp v122, v122, v122 quad_perm:[1,0,3,2] row_mask:0xf bank_mask:0xf bound_ctrl:1
	v_pk_fma_f32 v[116:117], v[164:165], v[60:61], v[116:117]
	v_pk_mul_f32 v[120:121], v[100:101], v[76:77] op_sel:[1,0]
	v_add_f32_dpp v122, v122, v122 quad_perm:[2,3,0,1] row_mask:0xf bank_mask:0xf bound_ctrl:1
	v_add_f32_e32 v204, v116, v117
	v_pk_fma_f32 v[166:167], v[166:167], v[66:67], v[118:119]
	v_add_f32_dpp v122, v122, v122 row_half_mirror row_mask:0xf bank_mask:0xf bound_ctrl:1
	v_pk_fma_f32 v[164:165], v[164:165], v[68:69], v[120:121]
	v_add_f32_dpp v222, v222, v222 row_half_mirror row_mask:0xf bank_mask:0xf bound_ctrl:1
	v_add_f32_dpp v122, v122, v122 row_mirror row_mask:0xf bank_mask:0xf bound_ctrl:1
	v_add_f32_dpp v223, v223, v223 row_half_mirror row_mask:0xf bank_mask:0xf bound_ctrl:1
	v_pk_fma_f32 v[166:167], v[70:71], v[122:123], v[166:167] op_sel_hi:[1,0,1]
	v_pk_fma_f32 v[164:165], v[72:73], v[122:123], v[164:165] op_sel_hi:[1,0,1]
	ds_read_b128 v[54:57], v124 offset:22016
	ds_read_b128 v[46:49], v124 offset:13824
	ds_read_b128 v[50:53], v124 offset:38400
	ds_read_b128 v[58:61], v124 offset:5632
	ds_read_b128 v[42:45], v124 offset:30208
	v_add_f32_dpp v220, v224, v224 row_half_mirror row_mask:0xf bank_mask:0xa bound_ctrl:1
	v_add_f32_dpp v221, v225, v225 row_half_mirror row_mask:0xf bank_mask:0xa bound_ctrl:1
	s_waitcnt lgkmcnt(11)
	v_pk_mul_f32 v[114:115], v[166:167], v[2:3]
	v_pk_fma_f32 v[114:115], v[164:165], v[4:5], v[114:115]
	v_add_f32_e32 v122, v114, v115
	v_pk_mul_f32 v[116:117], v[166:167], v[78:79]
	s_waitcnt lgkmcnt(10)
	v_pk_mul_f32 v[118:119], v[102:103], v[14:15] op_sel_hi:[0,1]
	v_add_f32_dpp v122, v122, v122 quad_perm:[1,0,3,2] row_mask:0xf bank_mask:0xf bound_ctrl:1
	v_pk_fma_f32 v[116:117], v[164:165], v[80:81], v[116:117]
	v_pk_mul_f32 v[120:121], v[102:103], v[16:17] op_sel_hi:[0,1]
	v_add_f32_dpp v122, v122, v122 quad_perm:[2,3,0,1] row_mask:0xf bank_mask:0xf bound_ctrl:1
	v_add_f32_e32 v205, v116, v117
	v_pk_fma_f32 v[166:167], v[166:167], v[6:7], v[118:119]
	v_add_f32_dpp v122, v122, v122 row_half_mirror row_mask:0xf bank_mask:0xf bound_ctrl:1
	v_pk_fma_f32 v[164:165], v[164:165], v[8:9], v[120:121]
	v_add_f32_dpp v222, v226, v226 row_half_mirror row_mask:0xf bank_mask:0xa bound_ctrl:1
	v_add_f32_dpp v122, v122, v122 row_mirror row_mask:0xf bank_mask:0xf bound_ctrl:1
	v_add_f32_dpp v223, v227, v227 row_half_mirror row_mask:0xf bank_mask:0xa bound_ctrl:1
	v_pk_fma_f32 v[166:167], v[10:11], v[122:123], v[166:167] op_sel_hi:[1,0,1]
	v_pk_fma_f32 v[164:165], v[12:13], v[122:123], v[164:165] op_sel_hi:[1,0,1]
	ds_read_b128 v[74:77], v124 offset:22272
	ds_read_b128 v[66:69], v124 offset:14080
	ds_read_b128 v[70:73], v124 offset:38656
	ds_read_b128 v[78:81], v124 offset:5888
	ds_read_b128 v[62:65], v124 offset:30464
	v_add_f32_dpp v220, v220, v220 quad_perm:[1,0,3,2] row_mask:0xf bank_mask:0xf bound_ctrl:1
	v_add_f32_dpp v221, v221, v221 quad_perm:[1,0,3,2] row_mask:0xf bank_mask:0xf bound_ctrl:1
	s_waitcnt lgkmcnt(10)
; #define LAS __attribute__((address_space(3)))
; __device__ __forceinline__ void phase_scan(const Params& p, LAS unsigned char* lds) {
;     ...
;                     for (int hb = 0; hb < 2; ++hb) {
;                         f32x4 vn[4];
; #pragma unroll
;                         for (int u = 0; u < 4; ++u) vn[u] = *(const LAS f32x4*)(sV + srow * 32 + ((16 * (hb + 1)) & 31) + 4 * u);
; #pragma unroll
;                         for (int u16 = 0; u16 < 16; ++u16) {
;                             const int s = 16 * hb + u16;
;                             const int sn = (s + 1) & 31;
;                             const f32x4 a_n = *(const LAS f32x4*)(sA + sn * 64), w_n = *(const LAS f32x4*)(sW + sn * 64), b_n = *(const LAS f32x4*)(sB + sn * 64);
;                             const f32x4 k_n = *(const LAS f32x4*)(sK + sn * 64), r_n = *(const LAS f32x4*)(sR + sn * 64);
;                             const float v = vq[u16 >> 2][u16 & 3];
;                             const f32x2 vv = {v, v};
;                             f32x2 pp = S01 * (f32x2){a_[0], a_[1]}; pp = S23 * (f32x2){a_[2], a_[3]} + pp;
;                             f32x2 yy = S01 * (f32x2){rp[0], rp[1]}; yy = S23 * (f32x2){rp[2], rp[3]} + yy;
;                             float sa = pp[0] + pp[1], y = yy[0] + yy[1];
;                             sa += dpp_f<0xB1>(sa); y += dpp_f<0xB1>(y);
;                             sa += dpp_f<0x4E>(sa); y += dpp_f<0x4E>(y);
;                             sa += dpp_f<0x141>(sa); y += dpp_f<0x141>(y);
;                             sa += dpp_f<0x140>(sa); y += dpp_f<0x140>(y);
;                             sY[((s - 1) & 31) * 16 + srow] = y;
;                             const f32x2 sv = {sa, sa};
;                             S01 = S01 * (f32x2){w_[0], w_[1]} + vv * (f32x2){k_[0], k_[1]};
;                             S23 = S23 * (f32x2){w_[2], w_[3]} + vv * (f32x2){k_[2], k_[3]};
;                             S01 = sv * (f32x2){b_[0], b_[1]} + S01;
;                             S23 = sv * (f32x2){b_[2], b_[3]} + S23;
;                             rp = r_;
;                             a_ = a_n; w_ = w_n; b_ = b_n; k_ = k_n; r_ = r_n;
;                         }
; #pragma unroll
;                         for (int u = 0; u < 4; ++u) vq[u] = vn[u];
	v_pk_mul_f32 v[114:115], v[166:167], v[22:23]
	v_pk_fma_f32 v[114:115], v[164:165], v[24:25], v[114:115]
	v_add_f32_e32 v122, v114, v115
	v_pk_mul_f32 v[116:117], v[166:167], v[18:19]
	v_pk_mul_f32 v[118:119], v[102:103], v[34:35] op_sel:[1,0]
	v_add_f32_dpp v122, v122, v122 quad_perm:[1,0,3,2] row_mask:0xf bank_mask:0xf bound_ctrl:1
	v_pk_fma_f32 v[116:117], v[164:165], v[20:21], v[116:117]
	v_pk_mul_f32 v[120:121], v[102:103], v[36:37] op_sel:[1,0]
	v_add_f32_dpp v122, v122, v122 quad_perm:[2,3,0,1] row_mask:0xf bank_mask:0xf bound_ctrl:1
	v_add_f32_e32 v206, v116, v117
	v_pk_fma_f32 v[166:167], v[166:167], v[26:27], v[118:119]
	v_add_f32_dpp v122, v122, v122 row_half_mirror row_mask:0xf bank_mask:0xf bound_ctrl:1
	v_pk_fma_f32 v[164:165], v[164:165], v[28:29], v[120:121]
	v_add_f32_dpp v222, v222, v222 quad_perm:[1,0,3,2] row_mask:0xf bank_mask:0xf bound_ctrl:1
	v_add_f32_dpp v122, v122, v122 row_mirror row_mask:0xf bank_mask:0xf bound_ctrl:1
	v_add_f32_dpp v223, v223, v223 quad_perm:[1,0,3,2] row_mask:0xf bank_mask:0xf bound_ctrl:1
	v_pk_fma_f32 v[166:167], v[30:31], v[122:123], v[166:167] op_sel_hi:[1,0,1]
	v_pk_fma_f32 v[164:165], v[32:33], v[122:123], v[164:165] op_sel_hi:[1,0,1]
	ds_read_b128 v[14:17], v124 offset:22528
	ds_read_b128 v[6:9], v124 offset:14336
	ds_read_b128 v[10:13], v124 offset:38912
	ds_read_b128 v[18:21], v124 offset:6144
	ds_read_b128 v[2:5], v124 offset:30720
	ds_read_b128 v[106:109], v125 offset:41056
	v_add_f32_dpp v220, v220, v220 quad_perm:[2,3,0,1] row_mask:0xf bank_mask:0xf bound_ctrl:1
	v_add_f32_dpp v221, v221, v221 quad_perm:[2,3,0,1] row_mask:0xf bank_mask:0xf bound_ctrl:1
	s_waitcnt lgkmcnt(11)
	v_pk_mul_f32 v[114:115], v[166:167], v[42:43]
	v_pk_fma_f32 v[114:115], v[164:165], v[44:45], v[114:115]
	v_add_f32_e32 v122, v114, v115
	v_pk_mul_f32 v[116:117], v[166:167], v[38:39]
	v_pk_mul_f32 v[118:119], v[104:105], v[54:55] op_sel_hi:[0,1]
	v_add_f32_dpp v122, v122, v122 quad_perm:[1,0,3,2] row_mask:0xf bank_mask:0xf bound_ctrl:1
	v_pk_fma_f32 v[116:117], v[164:165], v[40:41], v[116:117]
	v_pk_mul_f32 v[120:121], v[104:105], v[56:57] op_sel_hi:[0,1]
	v_add_f32_dpp v122, v122, v122 quad_perm:[2,3,0,1] row_mask:0xf bank_mask:0xf bound_ctrl:1
	v_add_f32_e32 v207, v116, v117
	v_pk_fma_f32 v[166:167], v[166:167], v[46:47], v[118:119]
	v_add_f32_dpp v122, v122, v122 row_half_mirror row_mask:0xf bank_mask:0xf bound_ctrl:1
	v_pk_fma_f32 v[164:165], v[164:165], v[48:49], v[120:121]
	v_add_f32_dpp v222, v222, v222 quad_perm:[2,3,0,1] row_mask:0xf bank_mask:0xf bound_ctrl:1
	v_add_f32_dpp v122, v122, v122 row_mirror row_mask:0xf bank_mask:0xf bound_ctrl:1
	v_add_f32_dpp v223, v223, v223 quad_perm:[2,3,0,1] row_mask:0xf bank_mask:0xf bound_ctrl:1
	v_pk_fma_f32 v[166:167], v[50:51], v[122:123], v[166:167] op_sel_hi:[1,0,1]
	v_pk_fma_f32 v[164:165], v[52:53], v[122:123], v[164:165] op_sel_hi:[1,0,1]
	ds_read_b128 v[34:37], v124 offset:22784
	ds_read_b128 v[26:29], v124 offset:14592
	ds_read_b128 v[30:33], v124 offset:39168
	ds_read_b128 v[38:41], v124 offset:6400
	ds_read_b128 v[22:25], v124 offset:30976
	v_cndmask_b32_e64 v202, v220, v221, s[34:35]
	v_cndmask_b32_e64 v202, v202, v222, s[56:57]
	s_waitcnt lgkmcnt(11)
	v_pk_mul_f32 v[114:115], v[166:167], v[62:63]
	v_pk_fma_f32 v[114:115], v[164:165], v[64:65], v[114:115]
	v_add_f32_e32 v122, v114, v115
	v_pk_mul_f32 v[116:117], v[166:167], v[58:59]
	v_pk_mul_f32 v[118:119], v[104:105], v[74:75] op_sel:[1,0]
	v_add_f32_dpp v122, v122, v122 quad_perm:[1,0,3,2] row_mask:0xf bank_mask:0xf bound_ctrl:1
	v_pk_fma_f32 v[116:117], v[164:165], v[60:61], v[116:117]
	v_pk_mul_f32 v[120:121], v[104:105], v[76:77] op_sel:[1,0]
	v_add_f32_dpp v122, v122, v122 quad_perm:[2,3,0,1] row_mask:0xf bank_mask:0xf bound_ctrl:1
	v_add_f32_e32 v208, v116, v117
	v_pk_fma_f32 v[166:167], v[166:167], v[66:67], v[118:119]
	v_add_f32_dpp v122, v122, v122 row_half_mirror row_mask:0xf bank_mask:0xf bound_ctrl:1
	v_pk_fma_f32 v[164:165], v[164:165], v[68:69], v[120:121]
	v_cndmask_b32_e64 v202, v202, v223, s[98:99]
	v_add_f32_dpp v122, v122, v122 row_mirror row_mask:0xf bank_mask:0xf bound_ctrl:1
	v_cvt_f16_f32_e32 v203, v202
	v_pk_fma_f32 v[166:167], v[70:71], v[122:123], v[166:167] op_sel_hi:[1,0,1]
	v_pk_fma_f32 v[164:165], v[72:73], v[122:123], v[164:165] op_sel_hi:[1,0,1]
	ds_read_b128 v[54:57], v124 offset:23040
	ds_read_b128 v[46:49], v124 offset:14848
	ds_read_b128 v[50:53], v124 offset:39424
	ds_read_b128 v[58:61], v124 offset:6656
	ds_read_b128 v[42:45], v124 offset:31232
	global_store_short v[126:127], v203, off
	v_lshl_add_u64 v[126:127], v[126:127], 0, s[100:101]
	s_waitcnt lgkmcnt(11)
	v_pk_mul_f32 v[114:115], v[166:167], v[2:3]
	v_pk_fma_f32 v[114:115], v[164:165], v[4:5], v[114:115]
	v_add_f32_e32 v122, v114, v115
	v_pk_mul_f32 v[116:117], v[166:167], v[78:79]
	s_waitcnt lgkmcnt(10)
	v_pk_mul_f32 v[118:119], v[106:107], v[14:15] op_sel_hi:[0,1]
	v_add_f32_dpp v122, v122, v122 quad_perm:[1,0,3,2] row_mask:0xf bank_mask:0xf bound_ctrl:1
	v_pk_fma_f32 v[116:117], v[164:165], v[80:81], v[116:117]
	v_pk_mul_f32 v[120:121], v[106:107], v[16:17] op_sel_hi:[0,1]
	v_add_f32_dpp v122, v122, v122 quad_perm:[2,3,0,1] row_mask:0xf bank_mask:0xf bound_ctrl:1
	v_add_f32_e32 v209, v116, v117
	v_pk_fma_f32 v[166:167], v[166:167], v[6:7], v[118:119]
	v_add_f32_dpp v122, v122, v122 row_half_mirror row_mask:0xf bank_mask:0xf bound_ctrl:1
	v_pk_fma_f32 v[164:165], v[164:165], v[8:9], v[120:121]
	s_nop 0
	v_add_f32_dpp v122, v122, v122 row_mirror row_mask:0xf bank_mask:0xf bound_ctrl:1
	v_pk_fma_f32 v[166:167], v[10:11], v[122:123], v[166:167] op_sel_hi:[1,0,1]
	v_pk_fma_f32 v[164:165], v[12:13], v[122:123], v[164:165] op_sel_hi:[1,0,1]
	ds_read_b128 v[74:77], v124 offset:23296
	ds_read_b128 v[66:69], v124 offset:15104
	ds_read_b128 v[70:73], v124 offset:39680
	ds_read_b128 v[78:81], v124 offset:6912
	ds_read_b128 v[62:65], v124 offset:31488
	s_waitcnt lgkmcnt(10)
; #define LAS __attribute__((address_space(3)))
; __device__ __forceinline__ void phase_scan(const Params& p, LAS unsigned char* lds) {
;     ...
;                     for (int hb = 0; hb < 2; ++hb) {
;                         f32x4 vn[4];
; #pragma unroll
;                         for (int u = 0; u < 4; ++u) vn[u] = *(const LAS f32x4*)(sV + srow * 32 + ((16 * (hb + 1)) & 31) + 4 * u);
; #pragma unroll
;                         for (int u16 = 0; u16 < 16; ++u16) {
;                             const int s = 16 * hb + u16;
;                             const int sn = (s + 1) & 31;
;                             const f32x4 a_n = *(const LAS f32x4*)(sA + sn * 64), w_n = *(const LAS f32x4*)(sW + sn * 64), b_n = *(const LAS f32x4*)(sB + sn * 64);
;                             const f32x4 k_n = *(const LAS f32x4*)(sK + sn * 64), r_n = *(const LAS f32x4*)(sR + sn * 64);
;                             const float v = vq[u16 >> 2][u16 & 3];
;                             const f32x2 vv = {v, v};
;                             f32x2 pp = S01 * (f32x2){a_[0], a_[1]}; pp = S23 * (f32x2){a_[2], a_[3]} + pp;
;                             f32x2 yy = S01 * (f32x2){rp[0], rp[1]}; yy = S23 * (f32x2){rp[2], rp[3]} + yy;
;                             float sa = pp[0] + pp[1], y = yy[0] + yy[1];
;                             sa += dpp_f<0xB1>(sa); y += dpp_f<0xB1>(y);
;                             sa += dpp_f<0x4E>(sa); y += dpp_f<0x4E>(y);
;                             sa += dpp_f<0x141>(sa); y += dpp_f<0x141>(y);
;                             sa += dpp_f<0x140>(sa); y += dpp_f<0x140>(y);
;                             sY[((s - 1) & 31) * 16 + srow] = y;
;                             const f32x2 sv = {sa, sa};
;                             S01 = S01 * (f32x2){w_[0], w_[1]} + vv * (f32x2){k_[0], k_[1]};
;                             S23 = S23 * (f32x2){w_[2], w_[3]} + vv * (f32x2){k_[2], k_[3]};
;                             S01 = sv * (f32x2){b_[0], b_[1]} + S01;
;                             S23 = sv * (f32x2){b_[2], b_[3]} + S23;
;                             rp = r_;
;                             a_ = a_n; w_ = w_n; b_ = b_n; k_ = k_n; r_ = r_n;
;                         }
; #pragma unroll
;                         for (int u = 0; u < 4; ++u) vq[u] = vn[u];
	v_pk_mul_f32 v[114:115], v[166:167], v[22:23]
	v_pk_fma_f32 v[114:115], v[164:165], v[24:25], v[114:115]
	v_add_f32_e32 v122, v114, v115
	v_pk_mul_f32 v[116:117], v[166:167], v[18:19]
	v_pk_mul_f32 v[118:119], v[106:107], v[34:35] op_sel:[1,0]
	v_add_f32_dpp v122, v122, v122 quad_perm:[1,0,3,2] row_mask:0xf bank_mask:0xf bound_ctrl:1
	v_pk_fma_f32 v[116:117], v[164:165], v[20:21], v[116:117]
	v_pk_mul_f32 v[120:121], v[106:107], v[36:37] op_sel:[1,0]
	v_add_f32_dpp v122, v122, v122 quad_perm:[2,3,0,1] row_mask:0xf bank_mask:0xf bound_ctrl:1
	v_add_f32_e32 v210, v116, v117
	v_pk_fma_f32 v[166:167], v[166:167], v[26:27], v[118:119]
	v_add_f32_dpp v122, v122, v122 row_half_mirror row_mask:0xf bank_mask:0xf bound_ctrl:1
	v_pk_fma_f32 v[164:165], v[164:165], v[28:29], v[120:121]
	s_nop 0
	v_add_f32_dpp v122, v122, v122 row_mirror row_mask:0xf bank_mask:0xf bound_ctrl:1
	v_pk_fma_f32 v[166:167], v[30:31], v[122:123], v[166:167] op_sel_hi:[1,0,1]
	v_pk_fma_f32 v[164:165], v[32:33], v[122:123], v[164:165] op_sel_hi:[1,0,1]
	ds_read_b128 v[14:17], v124 offset:23552
	ds_read_b128 v[6:9], v124 offset:15360
	ds_read_b128 v[10:13], v124 offset:39936
	ds_read_b128 v[18:21], v124 offset:7168
	ds_read_b128 v[2:5], v124 offset:31744
	ds_read_b128 v[110:113], v125 offset:41072
	s_waitcnt lgkmcnt(11)
	v_pk_mul_f32 v[114:115], v[166:167], v[42:43]
	v_pk_fma_f32 v[114:115], v[164:165], v[44:45], v[114:115]
	v_add_f32_e32 v122, v114, v115
	v_pk_mul_f32 v[116:117], v[166:167], v[38:39]
	v_pk_mul_f32 v[118:119], v[108:109], v[54:55] op_sel_hi:[0,1]
	v_add_f32_dpp v122, v122, v122 quad_perm:[1,0,3,2] row_mask:0xf bank_mask:0xf bound_ctrl:1
	v_pk_fma_f32 v[116:117], v[164:165], v[40:41], v[116:117]
	v_pk_mul_f32 v[120:121], v[108:109], v[56:57] op_sel_hi:[0,1]
	v_add_f32_dpp v122, v122, v122 quad_perm:[2,3,0,1] row_mask:0xf bank_mask:0xf bound_ctrl:1
	v_add_f32_e32 v211, v116, v117
	v_pk_fma_f32 v[166:167], v[166:167], v[46:47], v[118:119]
	v_add_f32_dpp v122, v122, v122 row_half_mirror row_mask:0xf bank_mask:0xf bound_ctrl:1
	v_pk_fma_f32 v[164:165], v[164:165], v[48:49], v[120:121]
	s_nop 0
	v_add_f32_dpp v122, v122, v122 row_mirror row_mask:0xf bank_mask:0xf bound_ctrl:1
	v_pk_fma_f32 v[166:167], v[50:51], v[122:123], v[166:167] op_sel_hi:[1,0,1]
	v_pk_fma_f32 v[164:165], v[52:53], v[122:123], v[164:165] op_sel_hi:[1,0,1]
	ds_read_b128 v[34:37], v124 offset:23808
	ds_read_b128 v[26:29], v124 offset:15616
	ds_read_b128 v[30:33], v124 offset:40192
	ds_read_b128 v[38:41], v124 offset:7424
	ds_read_b128 v[22:25], v124 offset:32000
	s_waitcnt lgkmcnt(11)
	v_pk_mul_f32 v[114:115], v[166:167], v[62:63]
	v_pk_fma_f32 v[114:115], v[164:165], v[64:65], v[114:115]
	v_add_f32_e32 v122, v114, v115
	v_pk_mul_f32 v[116:117], v[166:167], v[58:59]
	v_pk_mul_f32 v[118:119], v[108:109], v[74:75] op_sel:[1,0]
	v_add_f32_dpp v122, v122, v122 quad_perm:[1,0,3,2] row_mask:0xf bank_mask:0xf bound_ctrl:1
	v_pk_fma_f32 v[116:117], v[164:165], v[60:61], v[116:117]
	v_pk_mul_f32 v[120:121], v[108:109], v[76:77] op_sel:[1,0]
	v_add_f32_dpp v122, v122, v122 quad_perm:[2,3,0,1] row_mask:0xf bank_mask:0xf bound_ctrl:1
	v_add_f32_e32 v212, v116, v117
	v_pk_fma_f32 v[166:167], v[166:167], v[66:67], v[118:119]
	v_add_f32_dpp v122, v122, v122 row_half_mirror row_mask:0xf bank_mask:0xf bound_ctrl:1
	v_pk_fma_f32 v[164:165], v[164:165], v[68:69], v[120:121]
	s_nop 0
	v_add_f32_dpp v122, v122, v122 row_mirror row_mask:0xf bank_mask:0xf bound_ctrl:1
	v_pk_fma_f32 v[166:167], v[70:71], v[122:123], v[166:167] op_sel_hi:[1,0,1]
	v_pk_fma_f32 v[164:165], v[72:73], v[122:123], v[164:165] op_sel_hi:[1,0,1]
	ds_read_b128 v[54:57], v124 offset:24064
	ds_read_b128 v[46:49], v124 offset:15872
	ds_read_b128 v[50:53], v124 offset:40448
	ds_read_b128 v[58:61], v124 offset:7680
	ds_read_b128 v[42:45], v124 offset:32256
	s_waitcnt lgkmcnt(11)
	v_pk_mul_f32 v[114:115], v[166:167], v[2:3]
	v_pk_fma_f32 v[114:115], v[164:165], v[4:5], v[114:115]
	v_add_f32_e32 v122, v114, v115
	v_pk_mul_f32 v[116:117], v[166:167], v[78:79]
	s_waitcnt lgkmcnt(10)
	v_pk_mul_f32 v[118:119], v[110:111], v[14:15] op_sel_hi:[0,1]
	v_add_f32_dpp v122, v122, v122 quad_perm:[1,0,3,2] row_mask:0xf bank_mask:0xf bound_ctrl:1
	v_pk_fma_f32 v[116:117], v[164:165], v[80:81], v[116:117]
	v_pk_mul_f32 v[120:121], v[110:111], v[16:17] op_sel_hi:[0,1]
	v_add_f32_dpp v122, v122, v122 quad_perm:[2,3,0,1] row_mask:0xf bank_mask:0xf bound_ctrl:1
	v_add_f32_e32 v213, v116, v117
	v_pk_fma_f32 v[166:167], v[166:167], v[6:7], v[118:119]
	v_add_f32_dpp v122, v122, v122 row_half_mirror row_mask:0xf bank_mask:0xf bound_ctrl:1
	v_pk_fma_f32 v[164:165], v[164:165], v[8:9], v[120:121]
	s_nop 0
	v_add_f32_dpp v122, v122, v122 row_mirror row_mask:0xf bank_mask:0xf bound_ctrl:1
	v_pk_fma_f32 v[166:167], v[10:11], v[122:123], v[166:167] op_sel_hi:[1,0,1]
	v_pk_fma_f32 v[164:165], v[12:13], v[122:123], v[164:165] op_sel_hi:[1,0,1]
	ds_read_b128 v[74:77], v124 offset:24320
	ds_read_b128 v[66:69], v124 offset:16128
	ds_read_b128 v[70:73], v124 offset:40704
	ds_read_b128 v[78:81], v124 offset:7936
	ds_read_b128 v[62:65], v124 offset:32512
	s_waitcnt lgkmcnt(0)
	s_barrier
	s_add_i32 s81, s81, 1
	s_addk_i32 s82, 0x200
	s_cmpk_eq_i32 s81, 0x100
	s_cbranch_scc0 .Lscan_trip
	s_branch .LBB0_620
; #define LAS __attribute__((address_space(3)))
; template <int CTRL> __device__ __forceinline__ float dpp_f(float x) { return __int_as_float(__builtin_amdgcn_update_dpp(0, __float_as_int(x), CTRL, 0xf, 0xf, false)); }
; __device__ __forceinline__ void phase_scan(const Params& p, LAS unsigned char* lds) {
;     ...
;                         for (int u16 = 0; u16 < 16; ++u16) {
;                             const int s = 16 * hb + u16;
;                             const int sn = (s + 1) & 31;
;                             const f32x4 a_n = *(const LAS f32x4*)(sA + sn * 64), w_n = *(const LAS f32x4*)(sW + sn * 64), b_n = *(const LAS f32x4*)(sB + sn * 64);
;                             const f32x4 k_n = *(const LAS f32x4*)(sK + sn * 64), r_n = *(const LAS f32x4*)(sR + sn * 64);
;                             const float v = vq[u16 >> 2][u16 & 3];
;                             const f32x2 vv = {v, v};
;                             f32x2 pp = S01 * (f32x2){a_[0], a_[1]}; pp = S23 * (f32x2){a_[2], a_[3]} + pp;
;                             f32x2 yy = S01 * (f32x2){rp[0], rp[1]}; yy = S23 * (f32x2){rp[2], rp[3]} + yy;
;                             float sa = pp[0] + pp[1], y = yy[0] + yy[1];
;                             sa += dpp_f<0xB1>(sa); y += dpp_f<0xB1>(y);
;                             sa += dpp_f<0x4E>(sa); y += dpp_f<0x4E>(y);
;                             sa += dpp_f<0x141>(sa); y += dpp_f<0x141>(y);
;                             sa += dpp_f<0x140>(sa); y += dpp_f<0x140>(y);
;                             sY[((s - 1) & 31) * 16 + srow] = y;
;                             const f32x2 sv = {sa, sa};
;                             S01 = S01 * (f32x2){w_[0], w_[1]} + vv * (f32x2){k_[0], k_[1]};
;                             S23 = S23 * (f32x2){w_[2], w_[3]} + vv * (f32x2){k_[2], k_[3]};
;                             S01 = sv * (f32x2){b_[0], b_[1]} + S01;
;                             S23 = sv * (f32x2){b_[2], b_[3]} + S23;
;                             rp = r_;
;                             a_ = a_n; w_ = w_n; b_ = b_n; k_ = k_n; r_ = r_n;
;                         }
; #pragma unroll
;                         for (int u = 0; u < 4; ++u) vq[u] = vn[u];
;                     }
;                     { f32x2 yy = S01 * (f32x2){rp[0], rp[1]}; yy = S23 * (f32x2){rp[2], rp[3]} + yy; sY[31 * 16 + srow] = red16(yy[0] + yy[1]); }
.LBB0_620:
	s_mov_b64 s[10:11], 0
	s_cmp_eq_u64 s[0:1], 0
	s_cbranch_scc0 .LBB0_594
	s_setprio 1
	s_mov_b32 s14, 0x3fff3fff
	s_mov_b32 s15, s14
	v_pk_mul_f32 v[114:115], v[166:167], v[22:23]
	v_pk_fma_f32 v[114:115], v[164:165], v[24:25], v[114:115]
	v_add_f32_e32 v122, v114, v115
	v_pk_mul_f32 v[116:117], v[166:167], v[18:19]
	v_pk_mul_f32 v[118:119], v[110:111], v[34:35] op_sel:[1,0]
	v_add_f32_dpp v122, v122, v122 quad_perm:[1,0,3,2] row_mask:0xf bank_mask:0xf bound_ctrl:1
	v_pk_fma_f32 v[116:117], v[164:165], v[20:21], v[116:117]
	v_pk_mul_f32 v[120:121], v[110:111], v[36:37] op_sel:[1,0]
	v_add_f32_dpp v122, v122, v122 quad_perm:[2,3,0,1] row_mask:0xf bank_mask:0xf bound_ctrl:1
	v_add_f32_e32 v214, v116, v117
	v_pk_fma_f32 v[166:167], v[166:167], v[26:27], v[118:119]
	v_add_f32_dpp v122, v122, v122 row_half_mirror row_mask:0xf bank_mask:0xf bound_ctrl:1
	v_pk_fma_f32 v[164:165], v[164:165], v[28:29], v[120:121]
	v_add_f32_dpp v204, v204, v204 row_mirror row_mask:0xf bank_mask:0xf bound_ctrl:1
	v_add_f32_dpp v122, v122, v122 row_mirror row_mask:0xf bank_mask:0xf bound_ctrl:1
	v_add_f32_dpp v204, v212, v212 row_mirror row_mask:0xf bank_mask:0xc bound_ctrl:1
	v_pk_fma_f32 v[166:167], v[30:31], v[122:123], v[166:167] op_sel_hi:[1,0,1]
	v_pk_fma_f32 v[164:165], v[32:33], v[122:123], v[164:165] op_sel_hi:[1,0,1]
	v_add_f32_dpp v205, v205, v205 row_mirror row_mask:0xf bank_mask:0xf bound_ctrl:1
	v_add_f32_dpp v205, v213, v213 row_mirror row_mask:0xf bank_mask:0xc bound_ctrl:1
	v_pk_mul_f32 v[114:115], v[166:167], v[42:43]
	v_pk_fma_f32 v[114:115], v[164:165], v[44:45], v[114:115]
	v_add_f32_e32 v122, v114, v115
	v_pk_mul_f32 v[116:117], v[166:167], v[38:39]
	v_pk_mul_f32 v[118:119], v[112:113], v[54:55] op_sel_hi:[0,1]
	v_add_f32_dpp v122, v122, v122 quad_perm:[1,0,3,2] row_mask:0xf bank_mask:0xf bound_ctrl:1
	v_pk_fma_f32 v[116:117], v[164:165], v[40:41], v[116:117]
	v_pk_mul_f32 v[120:121], v[112:113], v[56:57] op_sel_hi:[0,1]
	v_add_f32_dpp v122, v122, v122 quad_perm:[2,3,0,1] row_mask:0xf bank_mask:0xf bound_ctrl:1
	v_add_f32_e32 v215, v116, v117
	v_pk_fma_f32 v[166:167], v[166:167], v[46:47], v[118:119]
	v_add_f32_dpp v122, v122, v122 row_half_mirror row_mask:0xf bank_mask:0xf bound_ctrl:1
	v_pk_fma_f32 v[164:165], v[164:165], v[48:49], v[120:121]
	v_add_f32_dpp v206, v206, v206 row_mirror row_mask:0xf bank_mask:0xf bound_ctrl:1
	v_add_f32_dpp v122, v122, v122 row_mirror row_mask:0xf bank_mask:0xf bound_ctrl:1
	v_add_f32_dpp v206, v214, v214 row_mirror row_mask:0xf bank_mask:0xc bound_ctrl:1
	v_pk_fma_f32 v[166:167], v[50:51], v[122:123], v[166:167] op_sel_hi:[1,0,1]
	v_pk_fma_f32 v[164:165], v[52:53], v[122:123], v[164:165] op_sel_hi:[1,0,1]
	v_add_f32_dpp v207, v207, v207 row_mirror row_mask:0xf bank_mask:0xf bound_ctrl:1
	v_add_f32_dpp v207, v215, v215 row_mirror row_mask:0xf bank_mask:0xc bound_ctrl:1
	v_pk_mul_f32 v[114:115], v[166:167], v[62:63]
	v_pk_fma_f32 v[114:115], v[164:165], v[64:65], v[114:115]
	v_add_f32_e32 v122, v114, v115
	v_pk_mul_f32 v[116:117], v[166:167], v[58:59]
	v_pk_mul_f32 v[118:119], v[112:113], v[74:75] op_sel:[1,0]
	v_add_f32_dpp v122, v122, v122 quad_perm:[1,0,3,2] row_mask:0xf bank_mask:0xf bound_ctrl:1
	v_pk_fma_f32 v[116:117], v[164:165], v[60:61], v[116:117]
	v_pk_mul_f32 v[120:121], v[112:113], v[76:77] op_sel:[1,0]
	v_add_f32_dpp v122, v122, v122 quad_perm:[2,3,0,1] row_mask:0xf bank_mask:0xf bound_ctrl:1
	v_add_f32_e32 v216, v116, v117
	v_pk_fma_f32 v[166:167], v[166:167], v[66:67], v[118:119]
	v_add_f32_dpp v122, v122, v122 row_half_mirror row_mask:0xf bank_mask:0xf bound_ctrl:1
	v_pk_fma_f32 v[164:165], v[164:165], v[68:69], v[120:121]
	v_add_f32_dpp v208, v208, v208 row_mirror row_mask:0xf bank_mask:0xf bound_ctrl:1
	v_add_f32_dpp v122, v122, v122 row_mirror row_mask:0xf bank_mask:0xf bound_ctrl:1
	v_add_f32_dpp v208, v216, v216 row_mirror row_mask:0xf bank_mask:0xc bound_ctrl:1
	v_pk_fma_f32 v[166:167], v[70:71], v[122:123], v[166:167] op_sel_hi:[1,0,1]
	v_pk_fma_f32 v[164:165], v[72:73], v[122:123], v[164:165] op_sel_hi:[1,0,1]
	v_pk_mul_f32 v[116:117], v[166:167], v[78:79]
	s_nop 0
	v_pk_fma_f32 v[116:117], v[164:165], v[80:81], v[116:117]
	s_nop 0
	v_add_f32_e32 v217, v116, v117
	v_mov_b32_e32 v218, 0
	v_mov_b32_e32 v219, 0
	s_nop 1
	v_add_f32_dpp v209, v209, v209 row_mirror row_mask:0xf bank_mask:0xf bound_ctrl:1
	v_add_f32_dpp v209, v217, v217 row_mirror row_mask:0xf bank_mask:0xc bound_ctrl:1
	v_add_f32_dpp v210, v210, v210 row_mirror row_mask:0xf bank_mask:0xf bound_ctrl:1
	v_add_f32_dpp v210, v218, v218 row_mirror row_mask:0xf bank_mask:0xc bound_ctrl:1
	v_add_f32_dpp v211, v211, v211 row_mirror row_mask:0xf bank_mask:0xf bound_ctrl:1
	v_add_f32_dpp v211, v219, v219 row_mirror row_mask:0xf bank_mask:0xc bound_ctrl:1
	s_nop 1
	v_add_f32_dpp v204, v204, v204 row_half_mirror row_mask:0xf bank_mask:0xf bound_ctrl:1
	v_add_f32_dpp v205, v205, v205 row_half_mirror row_mask:0xf bank_mask:0xf bound_ctrl:1
	v_add_f32_dpp v206, v206, v206 row_half_mirror row_mask:0xf bank_mask:0xf bound_ctrl:1
	v_add_f32_dpp v207, v207, v207 row_half_mirror row_mask:0xf bank_mask:0xf bound_ctrl:1
	v_add_f32_dpp v204, v208, v208 row_half_mirror row_mask:0xf bank_mask:0xa bound_ctrl:1
	v_add_f32_dpp v205, v209, v209 row_half_mirror row_mask:0xf bank_mask:0xa bound_ctrl:1
	v_add_f32_dpp v206, v210, v210 row_half_mirror row_mask:0xf bank_mask:0xa bound_ctrl:1
	v_add_f32_dpp v207, v211, v211 row_half_mirror row_mask:0xf bank_mask:0xa bound_ctrl:1
	v_add_f32_dpp v204, v204, v204 quad_perm:[1,0,3,2] row_mask:0xf bank_mask:0xf bound_ctrl:1
	v_add_f32_dpp v205, v205, v205 quad_perm:[1,0,3,2] row_mask:0xf bank_mask:0xf bound_ctrl:1
	v_add_f32_dpp v206, v206, v206 quad_perm:[1,0,3,2] row_mask:0xf bank_mask:0xf bound_ctrl:1
	v_add_f32_dpp v207, v207, v207 quad_perm:[1,0,3,2] row_mask:0xf bank_mask:0xf bound_ctrl:1
	v_add_f32_dpp v204, v204, v204 quad_perm:[2,3,0,1] row_mask:0xf bank_mask:0xf bound_ctrl:1
	v_add_f32_dpp v205, v205, v205 quad_perm:[2,3,0,1] row_mask:0xf bank_mask:0xf bound_ctrl:1
	v_add_f32_dpp v206, v206, v206 quad_perm:[2,3,0,1] row_mask:0xf bank_mask:0xf bound_ctrl:1
	v_add_f32_dpp v207, v207, v207 quad_perm:[2,3,0,1] row_mask:0xf bank_mask:0xf bound_ctrl:1
	v_cndmask_b32_e64 v202, v204, v205, s[34:35]
	v_cndmask_b32_e64 v202, v202, v206, s[56:57]
	v_cndmask_b32_e64 v202, v202, v207, s[98:99]
	v_cvt_f16_f32_e32 v203, v202
	s_mov_b64 exec, s[14:15]
	global_store_short v[128:129], v203, off
	s_mov_b64 exec, -1
	v_lshl_add_u64 v[128:129], v[128:129], 0, s[100:101]
	s_setprio 0
	s_branch .LBB0_594
